# P2(b): hand-written de-serialised sample-group LayerNorm/gate item (all loads up front, single wait chain) on top of the P1 K/V schedule
# baseline (speedup 1.0000x reference)
.LBB0_340:
	s_or_b64 exec, exec, s[8:9]
	s_add_u32 s38, s34, 0x17200000
	v_and_b32_e32 v73, 63, v126
	s_addc_u32 s39, s35, 0
	s_mov_b32 s8, 8
	s_mov_b32 s42, 8
	s_mov_b32 s6, 9
	s_mov_b32 s40, 9
	s_mov_b32 s10, 10
	s_mov_b32 s4, 11
	s_lshr_b32 s98, s24, 3
	s_and_b32 s99, s24, 7
	s_cselect_b32 s98, 0x1000, s98
	s_cmpk_lt_i32 s26, 0x100
	s_cselect_b32 s98, s24, s98
	s_cmpk_gt_i32 s98, 0xff
	v_lshlrev_b32_e32 v72, 3, v73
	s_cbranch_scc1 .LBB0_343
	s_ashr_i32 s43, s42, 31
	v_mbcnt_hi_u32_b32 v0, -1, v165
	s_lshl_b64 s[42:43], s[42:43], 3
	v_and_b32_e32 v1, 64, v0
	s_add_u32 s42, s0, s42
	v_add_u32_e32 v1, 64, v1
	v_xor_b32_e32 v2, 1, v0
	s_addc_u32 s43, s1, s43
	s_ashr_i32 s41, s40, 31
	v_cmp_lt_i32_e32 vcc, v2, v1
	s_lshl_b64 s[40:41], s[40:41], 3
	s_add_u32 s44, s0, s40
	v_cndmask_b32_e32 v2, v0, v2, vcc
	v_lshlrev_b32_e32 v128, 2, v2
	v_xor_b32_e32 v2, 2, v0
	s_addc_u32 s45, s1, s41
	s_ashr_i32 s11, s10, 31
	v_cmp_lt_i32_e32 vcc, v2, v1
	s_lshl_b64 s[10:11], s[10:11], 3
	s_add_u32 s46, s0, s10
	v_cndmask_b32_e32 v2, v0, v2, vcc
	v_lshlrev_b32_e32 v129, 2, v2
	v_xor_b32_e32 v2, 4, v0
	s_addc_u32 s47, s1, s11
	s_ashr_i32 s5, s4, 31
	v_cmp_lt_i32_e32 vcc, v2, v1
	s_lshl_b64 s[4:5], s[4:5], 3
	s_add_u32 s4, s0, s4
	v_cndmask_b32_e32 v2, v0, v2, vcc
	v_lshlrev_b32_e32 v130, 2, v2
	v_xor_b32_e32 v2, 8, v0
	s_addc_u32 s5, s1, s5
	s_load_dwordx2 s[10:11], s[42:43], 0x0
	s_load_dwordx2 s[40:41], s[44:45], 0x0
	s_nop 0
	s_load_dwordx2 s[42:43], s[46:47], 0x0
	s_load_dwordx2 s[44:45], s[4:5], 0x0
	v_cmp_lt_i32_e32 vcc, v2, v1
	s_add_u32 s7, s20, 0x5908000
	s_addc_u32 s9, s21, 0
	v_cndmask_b32_e32 v2, v0, v2, vcc
	v_lshlrev_b32_e32 v131, 2, v2
	v_xor_b32_e32 v2, 16, v0
	v_cmp_lt_i32_e32 vcc, v2, v1
	s_lshl_b32 s3, s2, 12
	s_lshl_b32 s4, s77, 9
	v_cndmask_b32_e32 v2, v0, v2, vcc
	v_lshlrev_b32_e32 v132, 2, v2
	v_xor_b32_e32 v2, 32, v0
	v_cmp_lt_i32_e32 vcc, v2, v1
	s_add_i32 s19, s3, s4
	s_lshl_b32 s19, s98, 9
	s_lshl_b32 s3, s2, 5
	s_lshl_b32 s4, s77, 2
	v_cndmask_b32_e32 v0, v0, v2, vcc
	v_mov_b32_e32 v75, 0
	v_lshlrev_b32_e32 v74, 4, v73
	s_add_i32 s29, s3, s4
	s_lshl_b32 s29, s98, 2
	s_mov_b32 s4, 0x358637bd
	v_lshlrev_b32_e32 v133, 2, v0
	v_lshl_add_u64 v[76:77], s[14:15], 0, v[74:75]
	s_lshl_b32 s25, s26, 12
	s_lshl_b32 s47, s26, 5
	v_lshlrev_b32_e32 v78, 1, v72
	v_mov_b32_e32 v79, v75
	s_movk_i32 s64, 0x5000
	s_mov_b32 s65, 0x9000
	s_mov_b32 s66, 0xe000
	s_mov_b32 s46, 0x3a800000
	v_mov_b64_e32 v[80:81], s[4:5]
	s_mov_b32 s67, 0x800000
	v_mov_b32_e32 v134, 0x4800
	s_mov_b32 s68, s98
	s_cmpk_lg_i32 s26, 0x100
	s_cbranch_scc1 .LBB0_342
	s_waitcnt lgkmcnt(0)
	s_and_b32 s56, s98, 1
	s_lshr_b32 s57, s98, 1
	s_sub_u32 s58, 0, s56
	s_mov_b32 s59, s58
	v_and_b32_e32 v254, 63, v164
	v_lshlrev_b32_e32 v160, 2, v254
	v_lshlrev_b32_e32 v162, 4, v254
	s_lshl_b32 s60, s56, 10
	v_add_u32_e32 v163, s60, v162
	v_add_u32_e32 v162, 0x800, v162
	v_lshlrev_b32_e32 v135, 5, v254
	s_lshl_b32 s60, s56, 11
	v_add_u32_e32 v135, s60, v135
	v_lshrrev_b32_e32 v255, 5, v254
	s_lshl_b32 s60, s56, 1
	v_add_u32_e32 v255, s60, v255
	v_lshlrev_b32_e32 v252, 16, v255
	v_lshlrev_b32_e32 v253, 9, v255
	s_mul_i32 s60, s57, 0x24000
	s_add_u32 s48, s34, s60
	s_addc_u32 s49, s35, 0
	s_add_u32 s48, s48, 0x15000000
	s_addc_u32 s49, s49, 0
	s_mov_b64 s[50:51], s[48:49]
	global_load_dwordx4 v[0:3], v162, s[48:49]
	global_load_dwordx4 v[4:7], v162, s[48:49] offset:1024
	s_add_u32 s48, s48, 0x4800
	s_addc_u32 s49, s49, 0
	global_load_dwordx4 v[8:11], v162, s[48:49]
	global_load_dwordx4 v[12:15], v162, s[48:49] offset:1024
	s_add_u32 s48, s48, 0x4800
	s_addc_u32 s49, s49, 0
	global_load_dwordx4 v[16:19], v162, s[48:49]
	global_load_dwordx4 v[20:23], v162, s[48:49] offset:1024
	s_add_u32 s48, s48, 0x4800
	s_addc_u32 s49, s49, 0
	global_load_dwordx4 v[24:27], v162, s[48:49]
	global_load_dwordx4 v[28:31], v162, s[48:49] offset:1024
	s_add_u32 s48, s48, 0x4800
	s_addc_u32 s49, s49, 0
	global_load_dwordx4 v[32:35], v162, s[48:49]
	global_load_dwordx4 v[36:39], v162, s[48:49] offset:1024
	s_add_u32 s48, s48, 0x4800
	s_addc_u32 s49, s49, 0
	global_load_dwordx4 v[40:43], v162, s[48:49]
	global_load_dwordx4 v[44:47], v162, s[48:49] offset:1024
	s_add_u32 s48, s48, 0x4800
	s_addc_u32 s49, s49, 0
	global_load_dwordx4 v[48:51], v162, s[48:49]
	global_load_dwordx4 v[52:55], v162, s[48:49] offset:1024
	s_add_u32 s48, s48, 0x4800
	s_addc_u32 s49, s49, 0
	global_load_dwordx4 v[56:59], v162, s[48:49]
	global_load_dwordx4 v[60:63], v162, s[48:49] offset:1024
	global_load_dwordx4 v[64:67], v135, s[10:11]
	global_load_dwordx4 v[68:71], v135, s[10:11] offset:16
	global_load_dwordx4 v[82:85], v135, s[40:41]
	global_load_dwordx4 v[86:89], v135, s[40:41] offset:16
	global_load_dwordx4 v[90:93], v253, s[44:45]
	global_load_dwordx4 v[94:97], v253, s[44:45] offset:16
	global_load_dwordx4 v[166:169], v252, s[42:43]
	global_load_dwordx4 v[170:173], v252, s[42:43] offset:16
	global_load_dwordx4 v[174:177], v252, s[42:43] offset:512
	global_load_dwordx4 v[178:181], v252, s[42:43] offset:528
	global_load_dwordx4 v[182:185], v252, s[42:43] offset:1024
	global_load_dwordx4 v[186:189], v252, s[42:43] offset:1040
	global_load_dwordx4 v[190:193], v252, s[42:43] offset:1536
	global_load_dwordx4 v[194:197], v252, s[42:43] offset:1552
	global_load_dwordx4 v[198:201], v252, s[42:43] offset:2048
	global_load_dwordx4 v[202:205], v252, s[42:43] offset:2064
	global_load_dwordx4 v[206:209], v252, s[42:43] offset:2560
	global_load_dwordx4 v[210:213], v252, s[42:43] offset:2576
	global_load_dwordx4 v[136:139], v252, s[42:43] offset:3072
	global_load_dwordx4 v[140:143], v252, s[42:43] offset:3088
	global_load_dwordx4 v[144:147], v252, s[42:43] offset:3584
	global_load_dwordx4 v[148:151], v252, s[42:43] offset:3600
	global_load_dwordx4 v[98:101], v163, s[50:51]
	s_add_u32 s50, s50, 0x4800
	s_addc_u32 s51, s51, 0
	global_load_dwordx4 v[102:105], v163, s[50:51]
	s_add_u32 s50, s50, 0x4800
	s_addc_u32 s51, s51, 0
	global_load_dwordx4 v[106:109], v163, s[50:51]
	s_add_u32 s50, s50, 0x4800
	s_addc_u32 s51, s51, 0
	global_load_dwordx4 v[110:113], v163, s[50:51]
	s_add_u32 s50, s50, 0x4800
	s_addc_u32 s51, s51, 0
	global_load_dwordx4 v[114:117], v163, s[50:51]
	s_add_u32 s50, s50, 0x4800
	s_addc_u32 s51, s51, 0
	global_load_dwordx4 v[118:121], v163, s[50:51]
	s_add_u32 s50, s50, 0x4800
	s_addc_u32 s51, s51, 0
	global_load_dwordx4 v[122:125], v163, s[50:51]
	s_add_u32 s50, s50, 0x4800
	s_addc_u32 s51, s51, 0
	global_load_dwordx4 v[214:217], v163, s[50:51]
	s_waitcnt vmcnt(30)
	v_mov_b32_e32 v236, 0
	v_lshlrev_b32_e32 v152, 16, v0
	v_lshlrev_b32_e32 v153, 16, v4
	v_add_f32_e32 v152, v152, v153
	v_add_f32_e32 v236, v236, v152
	v_and_b32_e32 v154, 0xffff0000, v0
	v_and_b32_e32 v155, 0xffff0000, v4
	v_add_f32_e32 v154, v154, v155
	v_add_f32_e32 v236, v236, v154
	v_lshlrev_b32_e32 v152, 16, v1
	v_lshlrev_b32_e32 v153, 16, v5
	v_add_f32_e32 v152, v152, v153
	v_add_f32_e32 v236, v236, v152
	v_and_b32_e32 v154, 0xffff0000, v1
	v_and_b32_e32 v155, 0xffff0000, v5
	v_add_f32_e32 v154, v154, v155
	v_add_f32_e32 v236, v236, v154
	v_lshlrev_b32_e32 v152, 16, v2
	v_lshlrev_b32_e32 v153, 16, v6
	v_add_f32_e32 v152, v152, v153
	v_add_f32_e32 v236, v236, v152
	v_and_b32_e32 v154, 0xffff0000, v2
	v_and_b32_e32 v155, 0xffff0000, v6
	v_add_f32_e32 v154, v154, v155
	v_add_f32_e32 v236, v236, v154
	v_lshlrev_b32_e32 v152, 16, v3
	v_lshlrev_b32_e32 v153, 16, v7
	v_add_f32_e32 v152, v152, v153
	v_add_f32_e32 v236, v236, v152
	v_and_b32_e32 v154, 0xffff0000, v3
	v_and_b32_e32 v155, 0xffff0000, v7
	v_add_f32_e32 v154, v154, v155
	v_add_f32_e32 v236, v236, v154
	v_mov_b32_e32 v237, 0
	v_lshlrev_b32_e32 v152, 16, v8
	v_lshlrev_b32_e32 v153, 16, v12
	v_add_f32_e32 v152, v152, v153
	v_add_f32_e32 v237, v237, v152
	v_and_b32_e32 v154, 0xffff0000, v8
	v_and_b32_e32 v155, 0xffff0000, v12
	v_add_f32_e32 v154, v154, v155
	v_add_f32_e32 v237, v237, v154
	v_lshlrev_b32_e32 v152, 16, v9
	v_lshlrev_b32_e32 v153, 16, v13
	v_add_f32_e32 v152, v152, v153
	v_add_f32_e32 v237, v237, v152
	v_and_b32_e32 v154, 0xffff0000, v9
	v_and_b32_e32 v155, 0xffff0000, v13
	v_add_f32_e32 v154, v154, v155
	v_add_f32_e32 v237, v237, v154
	v_lshlrev_b32_e32 v152, 16, v10
	v_lshlrev_b32_e32 v153, 16, v14
	v_add_f32_e32 v152, v152, v153
	v_add_f32_e32 v237, v237, v152
	v_and_b32_e32 v154, 0xffff0000, v10
	v_and_b32_e32 v155, 0xffff0000, v14
	v_add_f32_e32 v154, v154, v155
	v_add_f32_e32 v237, v237, v154
	v_lshlrev_b32_e32 v152, 16, v11
	v_lshlrev_b32_e32 v153, 16, v15
	v_add_f32_e32 v152, v152, v153
	v_add_f32_e32 v237, v237, v152
	v_and_b32_e32 v154, 0xffff0000, v11
	v_and_b32_e32 v155, 0xffff0000, v15
	v_add_f32_e32 v154, v154, v155
	v_add_f32_e32 v237, v237, v154
	v_mov_b32_e32 v238, 0
	v_lshlrev_b32_e32 v152, 16, v16
	v_lshlrev_b32_e32 v153, 16, v20
	v_add_f32_e32 v152, v152, v153
	v_add_f32_e32 v238, v238, v152
	v_and_b32_e32 v154, 0xffff0000, v16
	v_and_b32_e32 v155, 0xffff0000, v20
	v_add_f32_e32 v154, v154, v155
	v_add_f32_e32 v238, v238, v154
	v_lshlrev_b32_e32 v152, 16, v17
	v_lshlrev_b32_e32 v153, 16, v21
	v_add_f32_e32 v152, v152, v153
	v_add_f32_e32 v238, v238, v152
	v_and_b32_e32 v154, 0xffff0000, v17
	v_and_b32_e32 v155, 0xffff0000, v21
	v_add_f32_e32 v154, v154, v155
	v_add_f32_e32 v238, v238, v154
	v_lshlrev_b32_e32 v152, 16, v18
	v_lshlrev_b32_e32 v153, 16, v22
	v_add_f32_e32 v152, v152, v153
	v_add_f32_e32 v238, v238, v152
	v_and_b32_e32 v154, 0xffff0000, v18
	v_and_b32_e32 v155, 0xffff0000, v22
	v_add_f32_e32 v154, v154, v155
	v_add_f32_e32 v238, v238, v154
	v_lshlrev_b32_e32 v152, 16, v19
	v_lshlrev_b32_e32 v153, 16, v23
	v_add_f32_e32 v152, v152, v153
	v_add_f32_e32 v238, v238, v152
	v_and_b32_e32 v154, 0xffff0000, v19
	v_and_b32_e32 v155, 0xffff0000, v23
	v_add_f32_e32 v154, v154, v155
	v_add_f32_e32 v238, v238, v154
	v_mov_b32_e32 v239, 0
	v_lshlrev_b32_e32 v152, 16, v24
	v_lshlrev_b32_e32 v153, 16, v28
	v_add_f32_e32 v152, v152, v153
	v_add_f32_e32 v239, v239, v152
	v_and_b32_e32 v154, 0xffff0000, v24
	v_and_b32_e32 v155, 0xffff0000, v28
	v_add_f32_e32 v154, v154, v155
	v_add_f32_e32 v239, v239, v154
	v_lshlrev_b32_e32 v152, 16, v25
	v_lshlrev_b32_e32 v153, 16, v29
	v_add_f32_e32 v152, v152, v153
	v_add_f32_e32 v239, v239, v152
	v_and_b32_e32 v154, 0xffff0000, v25
	v_and_b32_e32 v155, 0xffff0000, v29
	v_add_f32_e32 v154, v154, v155
	v_add_f32_e32 v239, v239, v154
	v_lshlrev_b32_e32 v152, 16, v26
	v_lshlrev_b32_e32 v153, 16, v30
	v_add_f32_e32 v152, v152, v153
	v_add_f32_e32 v239, v239, v152
	v_and_b32_e32 v154, 0xffff0000, v26
	v_and_b32_e32 v155, 0xffff0000, v30
	v_add_f32_e32 v154, v154, v155
	v_add_f32_e32 v239, v239, v154
	v_lshlrev_b32_e32 v152, 16, v27
	v_lshlrev_b32_e32 v153, 16, v31
	v_add_f32_e32 v152, v152, v153
	v_add_f32_e32 v239, v239, v152
	v_and_b32_e32 v154, 0xffff0000, v27
	v_and_b32_e32 v155, 0xffff0000, v31
	v_add_f32_e32 v154, v154, v155
	v_add_f32_e32 v239, v239, v154
	v_mov_b32_e32 v240, 0
	v_lshlrev_b32_e32 v152, 16, v32
	v_lshlrev_b32_e32 v153, 16, v36
	v_add_f32_e32 v152, v152, v153
	v_add_f32_e32 v240, v240, v152
	v_and_b32_e32 v154, 0xffff0000, v32
	v_and_b32_e32 v155, 0xffff0000, v36
	v_add_f32_e32 v154, v154, v155
	v_add_f32_e32 v240, v240, v154
	v_lshlrev_b32_e32 v152, 16, v33
	v_lshlrev_b32_e32 v153, 16, v37
	v_add_f32_e32 v152, v152, v153
	v_add_f32_e32 v240, v240, v152
	v_and_b32_e32 v154, 0xffff0000, v33
	v_and_b32_e32 v155, 0xffff0000, v37
	v_add_f32_e32 v154, v154, v155
	v_add_f32_e32 v240, v240, v154
	v_lshlrev_b32_e32 v152, 16, v34
	v_lshlrev_b32_e32 v153, 16, v38
	v_add_f32_e32 v152, v152, v153
	v_add_f32_e32 v240, v240, v152
	v_and_b32_e32 v154, 0xffff0000, v34
	v_and_b32_e32 v155, 0xffff0000, v38
	v_add_f32_e32 v154, v154, v155
	v_add_f32_e32 v240, v240, v154
	v_lshlrev_b32_e32 v152, 16, v35
	v_lshlrev_b32_e32 v153, 16, v39
	v_add_f32_e32 v152, v152, v153
	v_add_f32_e32 v240, v240, v152
	v_and_b32_e32 v154, 0xffff0000, v35
	v_and_b32_e32 v155, 0xffff0000, v39
	v_add_f32_e32 v154, v154, v155
	v_add_f32_e32 v240, v240, v154
	v_mov_b32_e32 v241, 0
	v_lshlrev_b32_e32 v152, 16, v40
	v_lshlrev_b32_e32 v153, 16, v44
	v_add_f32_e32 v152, v152, v153
	v_add_f32_e32 v241, v241, v152
	v_and_b32_e32 v154, 0xffff0000, v40
	v_and_b32_e32 v155, 0xffff0000, v44
	v_add_f32_e32 v154, v154, v155
	v_add_f32_e32 v241, v241, v154
	v_lshlrev_b32_e32 v152, 16, v41
	v_lshlrev_b32_e32 v153, 16, v45
	v_add_f32_e32 v152, v152, v153
	v_add_f32_e32 v241, v241, v152
	v_and_b32_e32 v154, 0xffff0000, v41
	v_and_b32_e32 v155, 0xffff0000, v45
	v_add_f32_e32 v154, v154, v155
	v_add_f32_e32 v241, v241, v154
	v_lshlrev_b32_e32 v152, 16, v42
	v_lshlrev_b32_e32 v153, 16, v46
	v_add_f32_e32 v152, v152, v153
	v_add_f32_e32 v241, v241, v152
	v_and_b32_e32 v154, 0xffff0000, v42
	v_and_b32_e32 v155, 0xffff0000, v46
	v_add_f32_e32 v154, v154, v155
	v_add_f32_e32 v241, v241, v154
	v_lshlrev_b32_e32 v152, 16, v43
	v_lshlrev_b32_e32 v153, 16, v47
	v_add_f32_e32 v152, v152, v153
	v_add_f32_e32 v241, v241, v152
	v_and_b32_e32 v154, 0xffff0000, v43
	v_and_b32_e32 v155, 0xffff0000, v47
	v_add_f32_e32 v154, v154, v155
	v_add_f32_e32 v241, v241, v154
	v_mov_b32_e32 v242, 0
	v_lshlrev_b32_e32 v152, 16, v48
	v_lshlrev_b32_e32 v153, 16, v52
	v_add_f32_e32 v152, v152, v153
	v_add_f32_e32 v242, v242, v152
	v_and_b32_e32 v154, 0xffff0000, v48
	v_and_b32_e32 v155, 0xffff0000, v52
	v_add_f32_e32 v154, v154, v155
	v_add_f32_e32 v242, v242, v154
	v_lshlrev_b32_e32 v152, 16, v49
	v_lshlrev_b32_e32 v153, 16, v53
	v_add_f32_e32 v152, v152, v153
	v_add_f32_e32 v242, v242, v152
	v_and_b32_e32 v154, 0xffff0000, v49
	v_and_b32_e32 v155, 0xffff0000, v53
	v_add_f32_e32 v154, v154, v155
	v_add_f32_e32 v242, v242, v154
	v_lshlrev_b32_e32 v152, 16, v50
	v_lshlrev_b32_e32 v153, 16, v54
	v_add_f32_e32 v152, v152, v153
	v_add_f32_e32 v242, v242, v152
	v_and_b32_e32 v154, 0xffff0000, v50
	v_and_b32_e32 v155, 0xffff0000, v54
	v_add_f32_e32 v154, v154, v155
	v_add_f32_e32 v242, v242, v154
	v_lshlrev_b32_e32 v152, 16, v51
	v_lshlrev_b32_e32 v153, 16, v55
	v_add_f32_e32 v152, v152, v153
	v_add_f32_e32 v242, v242, v152
	v_and_b32_e32 v154, 0xffff0000, v51
	v_and_b32_e32 v155, 0xffff0000, v55
	v_add_f32_e32 v154, v154, v155
	v_add_f32_e32 v242, v242, v154
	v_mov_b32_e32 v243, 0
	v_lshlrev_b32_e32 v152, 16, v56
	v_lshlrev_b32_e32 v153, 16, v60
	v_add_f32_e32 v152, v152, v153
	v_add_f32_e32 v243, v243, v152
	v_and_b32_e32 v154, 0xffff0000, v56
	v_and_b32_e32 v155, 0xffff0000, v60
	v_add_f32_e32 v154, v154, v155
	v_add_f32_e32 v243, v243, v154
	v_lshlrev_b32_e32 v152, 16, v57
	v_lshlrev_b32_e32 v153, 16, v61
	v_add_f32_e32 v152, v152, v153
	v_add_f32_e32 v243, v243, v152
	v_and_b32_e32 v154, 0xffff0000, v57
	v_and_b32_e32 v155, 0xffff0000, v61
	v_add_f32_e32 v154, v154, v155
	v_add_f32_e32 v243, v243, v154
	v_lshlrev_b32_e32 v152, 16, v58
	v_lshlrev_b32_e32 v153, 16, v62
	v_add_f32_e32 v152, v152, v153
	v_add_f32_e32 v243, v243, v152
	v_and_b32_e32 v154, 0xffff0000, v58
	v_and_b32_e32 v155, 0xffff0000, v62
	v_add_f32_e32 v154, v154, v155
	v_add_f32_e32 v243, v243, v154
	v_lshlrev_b32_e32 v152, 16, v59
	v_lshlrev_b32_e32 v153, 16, v63
	v_add_f32_e32 v152, v152, v153
	v_add_f32_e32 v243, v243, v152
	v_and_b32_e32 v154, 0xffff0000, v59
	v_and_b32_e32 v155, 0xffff0000, v63
	v_add_f32_e32 v154, v154, v155
	v_add_f32_e32 v243, v243, v154
	v_xor_b32_e32 v161, 4, v160
	ds_bpermute_b32 v244, v161, v236
	ds_bpermute_b32 v245, v161, v237
	ds_bpermute_b32 v246, v161, v238
	ds_bpermute_b32 v247, v161, v239
	ds_bpermute_b32 v248, v161, v240
	ds_bpermute_b32 v249, v161, v241
	ds_bpermute_b32 v250, v161, v242
	ds_bpermute_b32 v251, v161, v243
	s_waitcnt lgkmcnt(0)
	v_add_f32_e32 v236, v236, v244
	v_add_f32_e32 v237, v237, v245
	v_add_f32_e32 v238, v238, v246
	v_add_f32_e32 v239, v239, v247
	v_add_f32_e32 v240, v240, v248
	v_add_f32_e32 v241, v241, v249
	v_add_f32_e32 v242, v242, v250
	v_add_f32_e32 v243, v243, v251
	v_xor_b32_e32 v161, 8, v160
	ds_bpermute_b32 v244, v161, v236
	ds_bpermute_b32 v245, v161, v237
	ds_bpermute_b32 v246, v161, v238
	ds_bpermute_b32 v247, v161, v239
	ds_bpermute_b32 v248, v161, v240
	ds_bpermute_b32 v249, v161, v241
	ds_bpermute_b32 v250, v161, v242
	ds_bpermute_b32 v251, v161, v243
	s_waitcnt lgkmcnt(0)
	v_add_f32_e32 v236, v236, v244
	v_add_f32_e32 v237, v237, v245
	v_add_f32_e32 v238, v238, v246
	v_add_f32_e32 v239, v239, v247
	v_add_f32_e32 v240, v240, v248
	v_add_f32_e32 v241, v241, v249
	v_add_f32_e32 v242, v242, v250
	v_add_f32_e32 v243, v243, v251
	v_xor_b32_e32 v161, 16, v160
	ds_bpermute_b32 v244, v161, v236
	ds_bpermute_b32 v245, v161, v237
	ds_bpermute_b32 v246, v161, v238
	ds_bpermute_b32 v247, v161, v239
	ds_bpermute_b32 v248, v161, v240
	ds_bpermute_b32 v249, v161, v241
	ds_bpermute_b32 v250, v161, v242
	ds_bpermute_b32 v251, v161, v243
	s_waitcnt lgkmcnt(0)
	v_add_f32_e32 v236, v236, v244
	v_add_f32_e32 v237, v237, v245
	v_add_f32_e32 v238, v238, v246
	v_add_f32_e32 v239, v239, v247
	v_add_f32_e32 v240, v240, v248
	v_add_f32_e32 v241, v241, v249
	v_add_f32_e32 v242, v242, v250
	v_add_f32_e32 v243, v243, v251
	v_xor_b32_e32 v161, 32, v160
	ds_bpermute_b32 v244, v161, v236
	ds_bpermute_b32 v245, v161, v237
	ds_bpermute_b32 v246, v161, v238
	ds_bpermute_b32 v247, v161, v239
	ds_bpermute_b32 v248, v161, v240
	ds_bpermute_b32 v249, v161, v241
	ds_bpermute_b32 v250, v161, v242
	ds_bpermute_b32 v251, v161, v243
	s_waitcnt lgkmcnt(0)
	v_add_f32_e32 v236, v236, v244
	v_add_f32_e32 v237, v237, v245
	v_add_f32_e32 v238, v238, v246
	v_add_f32_e32 v239, v239, v247
	v_add_f32_e32 v240, v240, v248
	v_add_f32_e32 v241, v241, v249
	v_add_f32_e32 v242, v242, v250
	v_add_f32_e32 v243, v243, v251
	v_xor_b32_e32 v161, 64, v160
	ds_bpermute_b32 v244, v161, v236
	ds_bpermute_b32 v245, v161, v237
	ds_bpermute_b32 v246, v161, v238
	ds_bpermute_b32 v247, v161, v239
	ds_bpermute_b32 v248, v161, v240
	ds_bpermute_b32 v249, v161, v241
	ds_bpermute_b32 v250, v161, v242
	ds_bpermute_b32 v251, v161, v243
	s_waitcnt lgkmcnt(0)
	v_add_f32_e32 v236, v236, v244
	v_add_f32_e32 v237, v237, v245
	v_add_f32_e32 v238, v238, v246
	v_add_f32_e32 v239, v239, v247
	v_add_f32_e32 v240, v240, v248
	v_add_f32_e32 v241, v241, v249
	v_add_f32_e32 v242, v242, v250
	v_add_f32_e32 v243, v243, v251
	v_xor_b32_e32 v161, 128, v160
	ds_bpermute_b32 v244, v161, v236
	ds_bpermute_b32 v245, v161, v237
	ds_bpermute_b32 v246, v161, v238
	ds_bpermute_b32 v247, v161, v239
	ds_bpermute_b32 v248, v161, v240
	ds_bpermute_b32 v249, v161, v241
	ds_bpermute_b32 v250, v161, v242
	ds_bpermute_b32 v251, v161, v243
	s_waitcnt lgkmcnt(0)
	v_add_f32_e32 v236, v236, v244
	v_add_f32_e32 v237, v237, v245
	v_add_f32_e32 v238, v238, v246
	v_add_f32_e32 v239, v239, v247
	v_add_f32_e32 v240, v240, v248
	v_add_f32_e32 v241, v241, v249
	v_add_f32_e32 v242, v242, v250
	v_add_f32_e32 v243, v243, v251
	v_mov_b32_e32 v159, 0x3a800000
	v_mul_f32_e32 v218, v236, v159
	v_mul_f32_e32 v219, v237, v159
	v_mul_f32_e32 v220, v238, v159
	v_mul_f32_e32 v221, v239, v159
	v_mul_f32_e32 v222, v240, v159
	v_mul_f32_e32 v223, v241, v159
	v_mul_f32_e32 v224, v242, v159
	v_mul_f32_e32 v225, v243, v159
	v_mov_b32_e32 v236, 0
	v_lshlrev_b32_e32 v152, 16, v0
	v_lshlrev_b32_e32 v153, 16, v4
	v_sub_f32_e32 v152, v152, v218
	v_sub_f32_e32 v153, v153, v218
	v_mul_f32_e32 v153, v153, v153
	v_fma_f32 v153, v152, v152, v153
	v_add_f32_e32 v236, v236, v153
	v_and_b32_e32 v152, 0xffff0000, v0
	v_and_b32_e32 v153, 0xffff0000, v4
	v_sub_f32_e32 v152, v152, v218
	v_sub_f32_e32 v153, v153, v218
	v_mul_f32_e32 v153, v153, v153
	v_fma_f32 v153, v152, v152, v153
	v_add_f32_e32 v236, v236, v153
	v_lshlrev_b32_e32 v152, 16, v1
	v_lshlrev_b32_e32 v153, 16, v5
	v_sub_f32_e32 v152, v152, v218
	v_sub_f32_e32 v153, v153, v218
	v_mul_f32_e32 v153, v153, v153
	v_fma_f32 v153, v152, v152, v153
	v_add_f32_e32 v236, v236, v153
	v_and_b32_e32 v152, 0xffff0000, v1
	v_and_b32_e32 v153, 0xffff0000, v5
	v_sub_f32_e32 v152, v152, v218
	v_sub_f32_e32 v153, v153, v218
	v_mul_f32_e32 v153, v153, v153
	v_fma_f32 v153, v152, v152, v153
	v_add_f32_e32 v236, v236, v153
	v_lshlrev_b32_e32 v152, 16, v2
	v_lshlrev_b32_e32 v153, 16, v6
	v_sub_f32_e32 v152, v152, v218
	v_sub_f32_e32 v153, v153, v218
	v_mul_f32_e32 v153, v153, v153
	v_fma_f32 v153, v152, v152, v153
	v_add_f32_e32 v236, v236, v153
	v_and_b32_e32 v152, 0xffff0000, v2
	v_and_b32_e32 v153, 0xffff0000, v6
	v_sub_f32_e32 v152, v152, v218
	v_sub_f32_e32 v153, v153, v218
	v_mul_f32_e32 v153, v153, v153
	v_fma_f32 v153, v152, v152, v153
	v_add_f32_e32 v236, v236, v153
	v_lshlrev_b32_e32 v152, 16, v3
	v_lshlrev_b32_e32 v153, 16, v7
	v_sub_f32_e32 v152, v152, v218
	v_sub_f32_e32 v153, v153, v218
	v_mul_f32_e32 v153, v153, v153
	v_fma_f32 v153, v152, v152, v153
	v_add_f32_e32 v236, v236, v153
	v_and_b32_e32 v152, 0xffff0000, v3
	v_and_b32_e32 v153, 0xffff0000, v7
	v_sub_f32_e32 v152, v152, v218
	v_sub_f32_e32 v153, v153, v218
	v_mul_f32_e32 v153, v153, v153
	v_fma_f32 v153, v152, v152, v153
	v_add_f32_e32 v236, v236, v153
	v_mov_b32_e32 v237, 0
	v_lshlrev_b32_e32 v152, 16, v8
	v_lshlrev_b32_e32 v153, 16, v12
	v_sub_f32_e32 v152, v152, v219
	v_sub_f32_e32 v153, v153, v219
	v_mul_f32_e32 v153, v153, v153
	v_fma_f32 v153, v152, v152, v153
	v_add_f32_e32 v237, v237, v153
	v_and_b32_e32 v152, 0xffff0000, v8
	v_and_b32_e32 v153, 0xffff0000, v12
	v_sub_f32_e32 v152, v152, v219
	v_sub_f32_e32 v153, v153, v219
	v_mul_f32_e32 v153, v153, v153
	v_fma_f32 v153, v152, v152, v153
	v_add_f32_e32 v237, v237, v153
	v_lshlrev_b32_e32 v152, 16, v9
	v_lshlrev_b32_e32 v153, 16, v13
	v_sub_f32_e32 v152, v152, v219
	v_sub_f32_e32 v153, v153, v219
	v_mul_f32_e32 v153, v153, v153
	v_fma_f32 v153, v152, v152, v153
	v_add_f32_e32 v237, v237, v153
	v_and_b32_e32 v152, 0xffff0000, v9
	v_and_b32_e32 v153, 0xffff0000, v13
	v_sub_f32_e32 v152, v152, v219
	v_sub_f32_e32 v153, v153, v219
	v_mul_f32_e32 v153, v153, v153
	v_fma_f32 v153, v152, v152, v153
	v_add_f32_e32 v237, v237, v153
	v_lshlrev_b32_e32 v152, 16, v10
	v_lshlrev_b32_e32 v153, 16, v14
	v_sub_f32_e32 v152, v152, v219
	v_sub_f32_e32 v153, v153, v219
	v_mul_f32_e32 v153, v153, v153
	v_fma_f32 v153, v152, v152, v153
	v_add_f32_e32 v237, v237, v153
	v_and_b32_e32 v152, 0xffff0000, v10
	v_and_b32_e32 v153, 0xffff0000, v14
	v_sub_f32_e32 v152, v152, v219
	v_sub_f32_e32 v153, v153, v219
	v_mul_f32_e32 v153, v153, v153
	v_fma_f32 v153, v152, v152, v153
	v_add_f32_e32 v237, v237, v153
	v_lshlrev_b32_e32 v152, 16, v11
	v_lshlrev_b32_e32 v153, 16, v15
	v_sub_f32_e32 v152, v152, v219
	v_sub_f32_e32 v153, v153, v219
	v_mul_f32_e32 v153, v153, v153
	v_fma_f32 v153, v152, v152, v153
	v_add_f32_e32 v237, v237, v153
	v_and_b32_e32 v152, 0xffff0000, v11
	v_and_b32_e32 v153, 0xffff0000, v15
	v_sub_f32_e32 v152, v152, v219
	v_sub_f32_e32 v153, v153, v219
	v_mul_f32_e32 v153, v153, v153
	v_fma_f32 v153, v152, v152, v153
	v_add_f32_e32 v237, v237, v153
	v_mov_b32_e32 v238, 0
	v_lshlrev_b32_e32 v152, 16, v16
	v_lshlrev_b32_e32 v153, 16, v20
	v_sub_f32_e32 v152, v152, v220
	v_sub_f32_e32 v153, v153, v220
	v_mul_f32_e32 v153, v153, v153
	v_fma_f32 v153, v152, v152, v153
	v_add_f32_e32 v238, v238, v153
	v_and_b32_e32 v152, 0xffff0000, v16
	v_and_b32_e32 v153, 0xffff0000, v20
	v_sub_f32_e32 v152, v152, v220
	v_sub_f32_e32 v153, v153, v220
	v_mul_f32_e32 v153, v153, v153
	v_fma_f32 v153, v152, v152, v153
	v_add_f32_e32 v238, v238, v153
	v_lshlrev_b32_e32 v152, 16, v17
	v_lshlrev_b32_e32 v153, 16, v21
	v_sub_f32_e32 v152, v152, v220
	v_sub_f32_e32 v153, v153, v220
	v_mul_f32_e32 v153, v153, v153
	v_fma_f32 v153, v152, v152, v153
	v_add_f32_e32 v238, v238, v153
	v_and_b32_e32 v152, 0xffff0000, v17
	v_and_b32_e32 v153, 0xffff0000, v21
	v_sub_f32_e32 v152, v152, v220
	v_sub_f32_e32 v153, v153, v220
	v_mul_f32_e32 v153, v153, v153
	v_fma_f32 v153, v152, v152, v153
	v_add_f32_e32 v238, v238, v153
	v_lshlrev_b32_e32 v152, 16, v18
	v_lshlrev_b32_e32 v153, 16, v22
	v_sub_f32_e32 v152, v152, v220
	v_sub_f32_e32 v153, v153, v220
	v_mul_f32_e32 v153, v153, v153
	v_fma_f32 v153, v152, v152, v153
	v_add_f32_e32 v238, v238, v153
	v_and_b32_e32 v152, 0xffff0000, v18
	v_and_b32_e32 v153, 0xffff0000, v22
	v_sub_f32_e32 v152, v152, v220
	v_sub_f32_e32 v153, v153, v220
	v_mul_f32_e32 v153, v153, v153
	v_fma_f32 v153, v152, v152, v153
	v_add_f32_e32 v238, v238, v153
	v_lshlrev_b32_e32 v152, 16, v19
	v_lshlrev_b32_e32 v153, 16, v23
	v_sub_f32_e32 v152, v152, v220
	v_sub_f32_e32 v153, v153, v220
	v_mul_f32_e32 v153, v153, v153
	v_fma_f32 v153, v152, v152, v153
	v_add_f32_e32 v238, v238, v153
	v_and_b32_e32 v152, 0xffff0000, v19
	v_and_b32_e32 v153, 0xffff0000, v23
	v_sub_f32_e32 v152, v152, v220
	v_sub_f32_e32 v153, v153, v220
	v_mul_f32_e32 v153, v153, v153
	v_fma_f32 v153, v152, v152, v153
	v_add_f32_e32 v238, v238, v153
	v_mov_b32_e32 v239, 0
	v_lshlrev_b32_e32 v152, 16, v24
	v_lshlrev_b32_e32 v153, 16, v28
	v_sub_f32_e32 v152, v152, v221
	v_sub_f32_e32 v153, v153, v221
	v_mul_f32_e32 v153, v153, v153
	v_fma_f32 v153, v152, v152, v153
	v_add_f32_e32 v239, v239, v153
	v_and_b32_e32 v152, 0xffff0000, v24
	v_and_b32_e32 v153, 0xffff0000, v28
	v_sub_f32_e32 v152, v152, v221
	v_sub_f32_e32 v153, v153, v221
	v_mul_f32_e32 v153, v153, v153
	v_fma_f32 v153, v152, v152, v153
	v_add_f32_e32 v239, v239, v153
	v_lshlrev_b32_e32 v152, 16, v25
	v_lshlrev_b32_e32 v153, 16, v29
	v_sub_f32_e32 v152, v152, v221
	v_sub_f32_e32 v153, v153, v221
	v_mul_f32_e32 v153, v153, v153
	v_fma_f32 v153, v152, v152, v153
	v_add_f32_e32 v239, v239, v153
	v_and_b32_e32 v152, 0xffff0000, v25
	v_and_b32_e32 v153, 0xffff0000, v29
	v_sub_f32_e32 v152, v152, v221
	v_sub_f32_e32 v153, v153, v221
	v_mul_f32_e32 v153, v153, v153
	v_fma_f32 v153, v152, v152, v153
	v_add_f32_e32 v239, v239, v153
	v_lshlrev_b32_e32 v152, 16, v26
	v_lshlrev_b32_e32 v153, 16, v30
	v_sub_f32_e32 v152, v152, v221
	v_sub_f32_e32 v153, v153, v221
	v_mul_f32_e32 v153, v153, v153
	v_fma_f32 v153, v152, v152, v153
	v_add_f32_e32 v239, v239, v153
	v_and_b32_e32 v152, 0xffff0000, v26
	v_and_b32_e32 v153, 0xffff0000, v30
	v_sub_f32_e32 v152, v152, v221
	v_sub_f32_e32 v153, v153, v221
	v_mul_f32_e32 v153, v153, v153
	v_fma_f32 v153, v152, v152, v153
	v_add_f32_e32 v239, v239, v153
	v_lshlrev_b32_e32 v152, 16, v27
	v_lshlrev_b32_e32 v153, 16, v31
	v_sub_f32_e32 v152, v152, v221
	v_sub_f32_e32 v153, v153, v221
	v_mul_f32_e32 v153, v153, v153
	v_fma_f32 v153, v152, v152, v153
	v_add_f32_e32 v239, v239, v153
	v_and_b32_e32 v152, 0xffff0000, v27
	v_and_b32_e32 v153, 0xffff0000, v31
	v_sub_f32_e32 v152, v152, v221
	v_sub_f32_e32 v153, v153, v221
	v_mul_f32_e32 v153, v153, v153
	v_fma_f32 v153, v152, v152, v153
	v_add_f32_e32 v239, v239, v153
	v_mov_b32_e32 v240, 0
	v_lshlrev_b32_e32 v152, 16, v32
	v_lshlrev_b32_e32 v153, 16, v36
	v_sub_f32_e32 v152, v152, v222
	v_sub_f32_e32 v153, v153, v222
	v_mul_f32_e32 v153, v153, v153
	v_fma_f32 v153, v152, v152, v153
	v_add_f32_e32 v240, v240, v153
	v_and_b32_e32 v152, 0xffff0000, v32
	v_and_b32_e32 v153, 0xffff0000, v36
	v_sub_f32_e32 v152, v152, v222
	v_sub_f32_e32 v153, v153, v222
	v_mul_f32_e32 v153, v153, v153
	v_fma_f32 v153, v152, v152, v153
	v_add_f32_e32 v240, v240, v153
	v_lshlrev_b32_e32 v152, 16, v33
	v_lshlrev_b32_e32 v153, 16, v37
	v_sub_f32_e32 v152, v152, v222
	v_sub_f32_e32 v153, v153, v222
	v_mul_f32_e32 v153, v153, v153
	v_fma_f32 v153, v152, v152, v153
	v_add_f32_e32 v240, v240, v153
	v_and_b32_e32 v152, 0xffff0000, v33
	v_and_b32_e32 v153, 0xffff0000, v37
	v_sub_f32_e32 v152, v152, v222
	v_sub_f32_e32 v153, v153, v222
	v_mul_f32_e32 v153, v153, v153
	v_fma_f32 v153, v152, v152, v153
	v_add_f32_e32 v240, v240, v153
	v_lshlrev_b32_e32 v152, 16, v34
	v_lshlrev_b32_e32 v153, 16, v38
	v_sub_f32_e32 v152, v152, v222
	v_sub_f32_e32 v153, v153, v222
	v_mul_f32_e32 v153, v153, v153
	v_fma_f32 v153, v152, v152, v153
	v_add_f32_e32 v240, v240, v153
	v_and_b32_e32 v152, 0xffff0000, v34
	v_and_b32_e32 v153, 0xffff0000, v38
	v_sub_f32_e32 v152, v152, v222
	v_sub_f32_e32 v153, v153, v222
	v_mul_f32_e32 v153, v153, v153
	v_fma_f32 v153, v152, v152, v153
	v_add_f32_e32 v240, v240, v153
	v_lshlrev_b32_e32 v152, 16, v35
	v_lshlrev_b32_e32 v153, 16, v39
	v_sub_f32_e32 v152, v152, v222
	v_sub_f32_e32 v153, v153, v222
	v_mul_f32_e32 v153, v153, v153
	v_fma_f32 v153, v152, v152, v153
	v_add_f32_e32 v240, v240, v153
	v_and_b32_e32 v152, 0xffff0000, v35
	v_and_b32_e32 v153, 0xffff0000, v39
	v_sub_f32_e32 v152, v152, v222
	v_sub_f32_e32 v153, v153, v222
	v_mul_f32_e32 v153, v153, v153
	v_fma_f32 v153, v152, v152, v153
	v_add_f32_e32 v240, v240, v153
	v_mov_b32_e32 v241, 0
	v_lshlrev_b32_e32 v152, 16, v40
	v_lshlrev_b32_e32 v153, 16, v44
	v_sub_f32_e32 v152, v152, v223
	v_sub_f32_e32 v153, v153, v223
	v_mul_f32_e32 v153, v153, v153
	v_fma_f32 v153, v152, v152, v153
	v_add_f32_e32 v241, v241, v153
	v_and_b32_e32 v152, 0xffff0000, v40
	v_and_b32_e32 v153, 0xffff0000, v44
	v_sub_f32_e32 v152, v152, v223
	v_sub_f32_e32 v153, v153, v223
	v_mul_f32_e32 v153, v153, v153
	v_fma_f32 v153, v152, v152, v153
	v_add_f32_e32 v241, v241, v153
	v_lshlrev_b32_e32 v152, 16, v41
	v_lshlrev_b32_e32 v153, 16, v45
	v_sub_f32_e32 v152, v152, v223
	v_sub_f32_e32 v153, v153, v223
	v_mul_f32_e32 v153, v153, v153
	v_fma_f32 v153, v152, v152, v153
	v_add_f32_e32 v241, v241, v153
	v_and_b32_e32 v152, 0xffff0000, v41
	v_and_b32_e32 v153, 0xffff0000, v45
	v_sub_f32_e32 v152, v152, v223
	v_sub_f32_e32 v153, v153, v223
	v_mul_f32_e32 v153, v153, v153
	v_fma_f32 v153, v152, v152, v153
	v_add_f32_e32 v241, v241, v153
	v_lshlrev_b32_e32 v152, 16, v42
	v_lshlrev_b32_e32 v153, 16, v46
	v_sub_f32_e32 v152, v152, v223
	v_sub_f32_e32 v153, v153, v223
	v_mul_f32_e32 v153, v153, v153
	v_fma_f32 v153, v152, v152, v153
	v_add_f32_e32 v241, v241, v153
	v_and_b32_e32 v152, 0xffff0000, v42
	v_and_b32_e32 v153, 0xffff0000, v46
	v_sub_f32_e32 v152, v152, v223
	v_sub_f32_e32 v153, v153, v223
	v_mul_f32_e32 v153, v153, v153
	v_fma_f32 v153, v152, v152, v153
	v_add_f32_e32 v241, v241, v153
	v_lshlrev_b32_e32 v152, 16, v43
	v_lshlrev_b32_e32 v153, 16, v47
	v_sub_f32_e32 v152, v152, v223
	v_sub_f32_e32 v153, v153, v223
	v_mul_f32_e32 v153, v153, v153
	v_fma_f32 v153, v152, v152, v153
	v_add_f32_e32 v241, v241, v153
	v_and_b32_e32 v152, 0xffff0000, v43
	v_and_b32_e32 v153, 0xffff0000, v47
	v_sub_f32_e32 v152, v152, v223
	v_sub_f32_e32 v153, v153, v223
	v_mul_f32_e32 v153, v153, v153
	v_fma_f32 v153, v152, v152, v153
	v_add_f32_e32 v241, v241, v153
	v_mov_b32_e32 v242, 0
	v_lshlrev_b32_e32 v152, 16, v48
	v_lshlrev_b32_e32 v153, 16, v52
	v_sub_f32_e32 v152, v152, v224
	v_sub_f32_e32 v153, v153, v224
	v_mul_f32_e32 v153, v153, v153
	v_fma_f32 v153, v152, v152, v153
	v_add_f32_e32 v242, v242, v153
	v_and_b32_e32 v152, 0xffff0000, v48
	v_and_b32_e32 v153, 0xffff0000, v52
	v_sub_f32_e32 v152, v152, v224
	v_sub_f32_e32 v153, v153, v224
	v_mul_f32_e32 v153, v153, v153
	v_fma_f32 v153, v152, v152, v153
	v_add_f32_e32 v242, v242, v153
	v_lshlrev_b32_e32 v152, 16, v49
	v_lshlrev_b32_e32 v153, 16, v53
	v_sub_f32_e32 v152, v152, v224
	v_sub_f32_e32 v153, v153, v224
	v_mul_f32_e32 v153, v153, v153
	v_fma_f32 v153, v152, v152, v153
	v_add_f32_e32 v242, v242, v153
	v_and_b32_e32 v152, 0xffff0000, v49
	v_and_b32_e32 v153, 0xffff0000, v53
	v_sub_f32_e32 v152, v152, v224
	v_sub_f32_e32 v153, v153, v224
	v_mul_f32_e32 v153, v153, v153
	v_fma_f32 v153, v152, v152, v153
	v_add_f32_e32 v242, v242, v153
	v_lshlrev_b32_e32 v152, 16, v50
	v_lshlrev_b32_e32 v153, 16, v54
	v_sub_f32_e32 v152, v152, v224
	v_sub_f32_e32 v153, v153, v224
	v_mul_f32_e32 v153, v153, v153
	v_fma_f32 v153, v152, v152, v153
	v_add_f32_e32 v242, v242, v153
	v_and_b32_e32 v152, 0xffff0000, v50
	v_and_b32_e32 v153, 0xffff0000, v54
	v_sub_f32_e32 v152, v152, v224
	v_sub_f32_e32 v153, v153, v224
	v_mul_f32_e32 v153, v153, v153
	v_fma_f32 v153, v152, v152, v153
	v_add_f32_e32 v242, v242, v153
	v_lshlrev_b32_e32 v152, 16, v51
	v_lshlrev_b32_e32 v153, 16, v55
	v_sub_f32_e32 v152, v152, v224
	v_sub_f32_e32 v153, v153, v224
	v_mul_f32_e32 v153, v153, v153
	v_fma_f32 v153, v152, v152, v153
	v_add_f32_e32 v242, v242, v153
	v_and_b32_e32 v152, 0xffff0000, v51
	v_and_b32_e32 v153, 0xffff0000, v55
	v_sub_f32_e32 v152, v152, v224
	v_sub_f32_e32 v153, v153, v224
	v_mul_f32_e32 v153, v153, v153
	v_fma_f32 v153, v152, v152, v153
	v_add_f32_e32 v242, v242, v153
	v_mov_b32_e32 v243, 0
	v_lshlrev_b32_e32 v152, 16, v56
	v_lshlrev_b32_e32 v153, 16, v60
	v_sub_f32_e32 v152, v152, v225
	v_sub_f32_e32 v153, v153, v225
	v_mul_f32_e32 v153, v153, v153
	v_fma_f32 v153, v152, v152, v153
	v_add_f32_e32 v243, v243, v153
	v_and_b32_e32 v152, 0xffff0000, v56
	v_and_b32_e32 v153, 0xffff0000, v60
	v_sub_f32_e32 v152, v152, v225
	v_sub_f32_e32 v153, v153, v225
	v_mul_f32_e32 v153, v153, v153
	v_fma_f32 v153, v152, v152, v153
	v_add_f32_e32 v243, v243, v153
	v_lshlrev_b32_e32 v152, 16, v57
	v_lshlrev_b32_e32 v153, 16, v61
	v_sub_f32_e32 v152, v152, v225
	v_sub_f32_e32 v153, v153, v225
	v_mul_f32_e32 v153, v153, v153
	v_fma_f32 v153, v152, v152, v153
	v_add_f32_e32 v243, v243, v153
	v_and_b32_e32 v152, 0xffff0000, v57
	v_and_b32_e32 v153, 0xffff0000, v61
	v_sub_f32_e32 v152, v152, v225
	v_sub_f32_e32 v153, v153, v225
	v_mul_f32_e32 v153, v153, v153
	v_fma_f32 v153, v152, v152, v153
	v_add_f32_e32 v243, v243, v153
	v_lshlrev_b32_e32 v152, 16, v58
	v_lshlrev_b32_e32 v153, 16, v62
	v_sub_f32_e32 v152, v152, v225
	v_sub_f32_e32 v153, v153, v225
	v_mul_f32_e32 v153, v153, v153
	v_fma_f32 v153, v152, v152, v153
	v_add_f32_e32 v243, v243, v153
	v_and_b32_e32 v152, 0xffff0000, v58
	v_and_b32_e32 v153, 0xffff0000, v62
	v_sub_f32_e32 v152, v152, v225
	v_sub_f32_e32 v153, v153, v225
	v_mul_f32_e32 v153, v153, v153
	v_fma_f32 v153, v152, v152, v153
	v_add_f32_e32 v243, v243, v153
	v_lshlrev_b32_e32 v152, 16, v59
	v_lshlrev_b32_e32 v153, 16, v63
	v_sub_f32_e32 v152, v152, v225
	v_sub_f32_e32 v153, v153, v225
	v_mul_f32_e32 v153, v153, v153
	v_fma_f32 v153, v152, v152, v153
	v_add_f32_e32 v243, v243, v153
	v_and_b32_e32 v152, 0xffff0000, v59
	v_and_b32_e32 v153, 0xffff0000, v63
	v_sub_f32_e32 v152, v152, v225
	v_sub_f32_e32 v153, v153, v225
	v_mul_f32_e32 v153, v153, v153
	v_fma_f32 v153, v152, v152, v153
	v_add_f32_e32 v243, v243, v153
	v_xor_b32_e32 v161, 4, v160
	ds_bpermute_b32 v244, v161, v236
	ds_bpermute_b32 v245, v161, v237
	ds_bpermute_b32 v246, v161, v238
	ds_bpermute_b32 v247, v161, v239
	ds_bpermute_b32 v248, v161, v240
	ds_bpermute_b32 v249, v161, v241
	ds_bpermute_b32 v250, v161, v242
	ds_bpermute_b32 v251, v161, v243
	s_waitcnt lgkmcnt(0)
	v_add_f32_e32 v236, v236, v244
	v_add_f32_e32 v237, v237, v245
	v_add_f32_e32 v238, v238, v246
	v_add_f32_e32 v239, v239, v247
	v_add_f32_e32 v240, v240, v248
	v_add_f32_e32 v241, v241, v249
	v_add_f32_e32 v242, v242, v250
	v_add_f32_e32 v243, v243, v251
	v_xor_b32_e32 v161, 8, v160
	ds_bpermute_b32 v244, v161, v236
	ds_bpermute_b32 v245, v161, v237
	ds_bpermute_b32 v246, v161, v238
	ds_bpermute_b32 v247, v161, v239
	ds_bpermute_b32 v248, v161, v240
	ds_bpermute_b32 v249, v161, v241
	ds_bpermute_b32 v250, v161, v242
	ds_bpermute_b32 v251, v161, v243
	s_waitcnt lgkmcnt(0)
	v_add_f32_e32 v236, v236, v244
	v_add_f32_e32 v237, v237, v245
	v_add_f32_e32 v238, v238, v246
	v_add_f32_e32 v239, v239, v247
	v_add_f32_e32 v240, v240, v248
	v_add_f32_e32 v241, v241, v249
	v_add_f32_e32 v242, v242, v250
	v_add_f32_e32 v243, v243, v251
	v_xor_b32_e32 v161, 16, v160
	ds_bpermute_b32 v244, v161, v236
	ds_bpermute_b32 v245, v161, v237
	ds_bpermute_b32 v246, v161, v238
	ds_bpermute_b32 v247, v161, v239
	ds_bpermute_b32 v248, v161, v240
	ds_bpermute_b32 v249, v161, v241
	ds_bpermute_b32 v250, v161, v242
	ds_bpermute_b32 v251, v161, v243
	s_waitcnt lgkmcnt(0)
	v_add_f32_e32 v236, v236, v244
	v_add_f32_e32 v237, v237, v245
	v_add_f32_e32 v238, v238, v246
	v_add_f32_e32 v239, v239, v247
	v_add_f32_e32 v240, v240, v248
	v_add_f32_e32 v241, v241, v249
	v_add_f32_e32 v242, v242, v250
	v_add_f32_e32 v243, v243, v251
	v_xor_b32_e32 v161, 32, v160
	ds_bpermute_b32 v244, v161, v236
	ds_bpermute_b32 v245, v161, v237
	ds_bpermute_b32 v246, v161, v238
	ds_bpermute_b32 v247, v161, v239
	ds_bpermute_b32 v248, v161, v240
	ds_bpermute_b32 v249, v161, v241
	ds_bpermute_b32 v250, v161, v242
	ds_bpermute_b32 v251, v161, v243
	s_waitcnt lgkmcnt(0)
	v_add_f32_e32 v236, v236, v244
	v_add_f32_e32 v237, v237, v245
	v_add_f32_e32 v238, v238, v246
	v_add_f32_e32 v239, v239, v247
	v_add_f32_e32 v240, v240, v248
	v_add_f32_e32 v241, v241, v249
	v_add_f32_e32 v242, v242, v250
	v_add_f32_e32 v243, v243, v251
	v_xor_b32_e32 v161, 64, v160
	ds_bpermute_b32 v244, v161, v236
	ds_bpermute_b32 v245, v161, v237
	ds_bpermute_b32 v246, v161, v238
	ds_bpermute_b32 v247, v161, v239
	ds_bpermute_b32 v248, v161, v240
	ds_bpermute_b32 v249, v161, v241
	ds_bpermute_b32 v250, v161, v242
	ds_bpermute_b32 v251, v161, v243
	s_waitcnt lgkmcnt(0)
	v_add_f32_e32 v236, v236, v244
	v_add_f32_e32 v237, v237, v245
	v_add_f32_e32 v238, v238, v246
	v_add_f32_e32 v239, v239, v247
	v_add_f32_e32 v240, v240, v248
	v_add_f32_e32 v241, v241, v249
	v_add_f32_e32 v242, v242, v250
	v_add_f32_e32 v243, v243, v251
	v_xor_b32_e32 v161, 128, v160
	ds_bpermute_b32 v244, v161, v236
	ds_bpermute_b32 v245, v161, v237
	ds_bpermute_b32 v246, v161, v238
	ds_bpermute_b32 v247, v161, v239
	ds_bpermute_b32 v248, v161, v240
	ds_bpermute_b32 v249, v161, v241
	ds_bpermute_b32 v250, v161, v242
	ds_bpermute_b32 v251, v161, v243
	s_waitcnt lgkmcnt(0)
	v_add_f32_e32 v236, v236, v244
	v_add_f32_e32 v237, v237, v245
	v_add_f32_e32 v238, v238, v246
	v_add_f32_e32 v239, v239, v247
	v_add_f32_e32 v240, v240, v248
	v_add_f32_e32 v241, v241, v249
	v_add_f32_e32 v242, v242, v250
	v_add_f32_e32 v243, v243, v251
	v_mov_b32_e32 v158, 0x358637bd
	v_fma_f32 v228, v236, v159, v158
	v_rsq_f32_e32 v228, v228
	v_fma_f32 v229, v237, v159, v158
	v_rsq_f32_e32 v229, v229
	v_fma_f32 v230, v238, v159, v158
	v_rsq_f32_e32 v230, v230
	v_fma_f32 v231, v239, v159, v158
	v_rsq_f32_e32 v231, v231
	v_fma_f32 v232, v240, v159, v158
	v_rsq_f32_e32 v232, v232
	v_fma_f32 v233, v241, v159, v158
	v_rsq_f32_e32 v233, v233
	v_fma_f32 v234, v242, v159, v158
	v_rsq_f32_e32 v234, v234
	v_fma_f32 v235, v243, v159, v158
	v_rsq_f32_e32 v235, v235
	s_waitcnt vmcnt(26)
	v_cndmask_b32_e64 v152, v0, v4, s[58:59]
	v_cndmask_b32_e64 v153, v1, v5, s[58:59]
	v_cndmask_b32_e64 v154, v2, v6, s[58:59]
	v_cndmask_b32_e64 v155, v3, v7, s[58:59]
	v_lshlrev_b32_e32 v156, 16, v152
	v_sub_f32_e32 v156, v156, v218
	v_mul_f32_e32 v156, v156, v228
	v_fma_f32 v0, v156, v64, v82
	v_and_b32_e32 v156, 0xffff0000, v152
	v_sub_f32_e32 v156, v156, v218
	v_mul_f32_e32 v156, v156, v228
	v_fma_f32 v1, v156, v65, v83
	v_lshlrev_b32_e32 v156, 16, v153
	v_sub_f32_e32 v156, v156, v218
	v_mul_f32_e32 v156, v156, v228
	v_fma_f32 v2, v156, v66, v84
	v_and_b32_e32 v156, 0xffff0000, v153
	v_sub_f32_e32 v156, v156, v218
	v_mul_f32_e32 v156, v156, v228
	v_fma_f32 v3, v156, v67, v85
	v_lshlrev_b32_e32 v156, 16, v154
	v_sub_f32_e32 v156, v156, v218
	v_mul_f32_e32 v156, v156, v228
	v_fma_f32 v4, v156, v68, v86
	v_and_b32_e32 v156, 0xffff0000, v154
	v_sub_f32_e32 v156, v156, v218
	v_mul_f32_e32 v156, v156, v228
	v_fma_f32 v5, v156, v69, v87
	v_lshlrev_b32_e32 v156, 16, v155
	v_sub_f32_e32 v156, v156, v218
	v_mul_f32_e32 v156, v156, v228
	v_fma_f32 v6, v156, v70, v88
	v_and_b32_e32 v156, 0xffff0000, v155
	v_sub_f32_e32 v156, v156, v218
	v_mul_f32_e32 v156, v156, v228
	v_fma_f32 v7, v156, v71, v89
	v_cndmask_b32_e64 v152, v8, v12, s[58:59]
	v_cndmask_b32_e64 v153, v9, v13, s[58:59]
	v_cndmask_b32_e64 v154, v10, v14, s[58:59]
	v_cndmask_b32_e64 v155, v11, v15, s[58:59]
	v_lshlrev_b32_e32 v156, 16, v152
	v_sub_f32_e32 v156, v156, v219
	v_mul_f32_e32 v156, v156, v229
	v_fma_f32 v8, v156, v64, v82
	v_and_b32_e32 v156, 0xffff0000, v152
	v_sub_f32_e32 v156, v156, v219
	v_mul_f32_e32 v156, v156, v229
	v_fma_f32 v9, v156, v65, v83
	v_lshlrev_b32_e32 v156, 16, v153
	v_sub_f32_e32 v156, v156, v219
	v_mul_f32_e32 v156, v156, v229
	v_fma_f32 v10, v156, v66, v84
	v_and_b32_e32 v156, 0xffff0000, v153
	v_sub_f32_e32 v156, v156, v219
	v_mul_f32_e32 v156, v156, v229
	v_fma_f32 v11, v156, v67, v85
	v_lshlrev_b32_e32 v156, 16, v154
	v_sub_f32_e32 v156, v156, v219
	v_mul_f32_e32 v156, v156, v229
	v_fma_f32 v12, v156, v68, v86
	v_and_b32_e32 v156, 0xffff0000, v154
	v_sub_f32_e32 v156, v156, v219
	v_mul_f32_e32 v156, v156, v229
	v_fma_f32 v13, v156, v69, v87
	v_lshlrev_b32_e32 v156, 16, v155
	v_sub_f32_e32 v156, v156, v219
	v_mul_f32_e32 v156, v156, v229
	v_fma_f32 v14, v156, v70, v88
	v_and_b32_e32 v156, 0xffff0000, v155
	v_sub_f32_e32 v156, v156, v219
	v_mul_f32_e32 v156, v156, v229
	v_fma_f32 v15, v156, v71, v89
	v_cndmask_b32_e64 v152, v16, v20, s[58:59]
	v_cndmask_b32_e64 v153, v17, v21, s[58:59]
	v_cndmask_b32_e64 v154, v18, v22, s[58:59]
	v_cndmask_b32_e64 v155, v19, v23, s[58:59]
	v_lshlrev_b32_e32 v156, 16, v152
	v_sub_f32_e32 v156, v156, v220
	v_mul_f32_e32 v156, v156, v230
	v_fma_f32 v16, v156, v64, v82
	v_and_b32_e32 v156, 0xffff0000, v152
	v_sub_f32_e32 v156, v156, v220
	v_mul_f32_e32 v156, v156, v230
	v_fma_f32 v17, v156, v65, v83
	v_lshlrev_b32_e32 v156, 16, v153
	v_sub_f32_e32 v156, v156, v220
	v_mul_f32_e32 v156, v156, v230
	v_fma_f32 v18, v156, v66, v84
	v_and_b32_e32 v156, 0xffff0000, v153
	v_sub_f32_e32 v156, v156, v220
	v_mul_f32_e32 v156, v156, v230
	v_fma_f32 v19, v156, v67, v85
	v_lshlrev_b32_e32 v156, 16, v154
	v_sub_f32_e32 v156, v156, v220
	v_mul_f32_e32 v156, v156, v230
	v_fma_f32 v20, v156, v68, v86
	v_and_b32_e32 v156, 0xffff0000, v154
	v_sub_f32_e32 v156, v156, v220
	v_mul_f32_e32 v156, v156, v230
	v_fma_f32 v21, v156, v69, v87
	v_lshlrev_b32_e32 v156, 16, v155
	v_sub_f32_e32 v156, v156, v220
	v_mul_f32_e32 v156, v156, v230
	v_fma_f32 v22, v156, v70, v88
	v_and_b32_e32 v156, 0xffff0000, v155
	v_sub_f32_e32 v156, v156, v220
	v_mul_f32_e32 v156, v156, v230
	v_fma_f32 v23, v156, v71, v89
	v_cndmask_b32_e64 v152, v24, v28, s[58:59]
	v_cndmask_b32_e64 v153, v25, v29, s[58:59]
	v_cndmask_b32_e64 v154, v26, v30, s[58:59]
	v_cndmask_b32_e64 v155, v27, v31, s[58:59]
	v_lshlrev_b32_e32 v156, 16, v152
	v_sub_f32_e32 v156, v156, v221
	v_mul_f32_e32 v156, v156, v231
	v_fma_f32 v24, v156, v64, v82
	v_and_b32_e32 v156, 0xffff0000, v152
	v_sub_f32_e32 v156, v156, v221
	v_mul_f32_e32 v156, v156, v231
	v_fma_f32 v25, v156, v65, v83
	v_lshlrev_b32_e32 v156, 16, v153
	v_sub_f32_e32 v156, v156, v221
	v_mul_f32_e32 v156, v156, v231
	v_fma_f32 v26, v156, v66, v84
	v_and_b32_e32 v156, 0xffff0000, v153
	v_sub_f32_e32 v156, v156, v221
	v_mul_f32_e32 v156, v156, v231
	v_fma_f32 v27, v156, v67, v85
	v_lshlrev_b32_e32 v156, 16, v154
	v_sub_f32_e32 v156, v156, v221
	v_mul_f32_e32 v156, v156, v231
	v_fma_f32 v28, v156, v68, v86
	v_and_b32_e32 v156, 0xffff0000, v154
	v_sub_f32_e32 v156, v156, v221
	v_mul_f32_e32 v156, v156, v231
	v_fma_f32 v29, v156, v69, v87
	v_lshlrev_b32_e32 v156, 16, v155
	v_sub_f32_e32 v156, v156, v221
	v_mul_f32_e32 v156, v156, v231
	v_fma_f32 v30, v156, v70, v88
	v_and_b32_e32 v156, 0xffff0000, v155
	v_sub_f32_e32 v156, v156, v221
	v_mul_f32_e32 v156, v156, v231
	v_fma_f32 v31, v156, v71, v89
	v_cndmask_b32_e64 v152, v32, v36, s[58:59]
	v_cndmask_b32_e64 v153, v33, v37, s[58:59]
	v_cndmask_b32_e64 v154, v34, v38, s[58:59]
	v_cndmask_b32_e64 v155, v35, v39, s[58:59]
	v_lshlrev_b32_e32 v156, 16, v152
	v_sub_f32_e32 v156, v156, v222
	v_mul_f32_e32 v156, v156, v232
	v_fma_f32 v32, v156, v64, v82
	v_and_b32_e32 v156, 0xffff0000, v152
	v_sub_f32_e32 v156, v156, v222
	v_mul_f32_e32 v156, v156, v232
	v_fma_f32 v33, v156, v65, v83
	v_lshlrev_b32_e32 v156, 16, v153
	v_sub_f32_e32 v156, v156, v222
	v_mul_f32_e32 v156, v156, v232
	v_fma_f32 v34, v156, v66, v84
	v_and_b32_e32 v156, 0xffff0000, v153
	v_sub_f32_e32 v156, v156, v222
	v_mul_f32_e32 v156, v156, v232
	v_fma_f32 v35, v156, v67, v85
	v_lshlrev_b32_e32 v156, 16, v154
	v_sub_f32_e32 v156, v156, v222
	v_mul_f32_e32 v156, v156, v232
	v_fma_f32 v36, v156, v68, v86
	v_and_b32_e32 v156, 0xffff0000, v154
	v_sub_f32_e32 v156, v156, v222
	v_mul_f32_e32 v156, v156, v232
	v_fma_f32 v37, v156, v69, v87
	v_lshlrev_b32_e32 v156, 16, v155
	v_sub_f32_e32 v156, v156, v222
	v_mul_f32_e32 v156, v156, v232
	v_fma_f32 v38, v156, v70, v88
	v_and_b32_e32 v156, 0xffff0000, v155
	v_sub_f32_e32 v156, v156, v222
	v_mul_f32_e32 v156, v156, v232
	v_fma_f32 v39, v156, v71, v89
	v_cndmask_b32_e64 v152, v40, v44, s[58:59]
	v_cndmask_b32_e64 v153, v41, v45, s[58:59]
	v_cndmask_b32_e64 v154, v42, v46, s[58:59]
	v_cndmask_b32_e64 v155, v43, v47, s[58:59]
	v_lshlrev_b32_e32 v156, 16, v152
	v_sub_f32_e32 v156, v156, v223
	v_mul_f32_e32 v156, v156, v233
	v_fma_f32 v40, v156, v64, v82
	v_and_b32_e32 v156, 0xffff0000, v152
	v_sub_f32_e32 v156, v156, v223
	v_mul_f32_e32 v156, v156, v233
	v_fma_f32 v41, v156, v65, v83
	v_lshlrev_b32_e32 v156, 16, v153
	v_sub_f32_e32 v156, v156, v223
	v_mul_f32_e32 v156, v156, v233
	v_fma_f32 v42, v156, v66, v84
	v_and_b32_e32 v156, 0xffff0000, v153
	v_sub_f32_e32 v156, v156, v223
	v_mul_f32_e32 v156, v156, v233
	v_fma_f32 v43, v156, v67, v85
	v_lshlrev_b32_e32 v156, 16, v154
	v_sub_f32_e32 v156, v156, v223
	v_mul_f32_e32 v156, v156, v233
	v_fma_f32 v44, v156, v68, v86
	v_and_b32_e32 v156, 0xffff0000, v154
	v_sub_f32_e32 v156, v156, v223
	v_mul_f32_e32 v156, v156, v233
	v_fma_f32 v45, v156, v69, v87
	v_lshlrev_b32_e32 v156, 16, v155
	v_sub_f32_e32 v156, v156, v223
	v_mul_f32_e32 v156, v156, v233
	v_fma_f32 v46, v156, v70, v88
	v_and_b32_e32 v156, 0xffff0000, v155
	v_sub_f32_e32 v156, v156, v223
	v_mul_f32_e32 v156, v156, v233
	v_fma_f32 v47, v156, v71, v89
	v_cndmask_b32_e64 v152, v48, v52, s[58:59]
	v_cndmask_b32_e64 v153, v49, v53, s[58:59]
	v_cndmask_b32_e64 v154, v50, v54, s[58:59]
	v_cndmask_b32_e64 v155, v51, v55, s[58:59]
	v_lshlrev_b32_e32 v156, 16, v152
	v_sub_f32_e32 v156, v156, v224
	v_mul_f32_e32 v156, v156, v234
	v_fma_f32 v48, v156, v64, v82
	v_and_b32_e32 v156, 0xffff0000, v152
	v_sub_f32_e32 v156, v156, v224
	v_mul_f32_e32 v156, v156, v234
	v_fma_f32 v49, v156, v65, v83
	v_lshlrev_b32_e32 v156, 16, v153
	v_sub_f32_e32 v156, v156, v224
	v_mul_f32_e32 v156, v156, v234
	v_fma_f32 v50, v156, v66, v84
	v_and_b32_e32 v156, 0xffff0000, v153
	v_sub_f32_e32 v156, v156, v224
	v_mul_f32_e32 v156, v156, v234
	v_fma_f32 v51, v156, v67, v85
	v_lshlrev_b32_e32 v156, 16, v154
	v_sub_f32_e32 v156, v156, v224
	v_mul_f32_e32 v156, v156, v234
	v_fma_f32 v52, v156, v68, v86
	v_and_b32_e32 v156, 0xffff0000, v154
	v_sub_f32_e32 v156, v156, v224
	v_mul_f32_e32 v156, v156, v234
	v_fma_f32 v53, v156, v69, v87
	v_lshlrev_b32_e32 v156, 16, v155
	v_sub_f32_e32 v156, v156, v224
	v_mul_f32_e32 v156, v156, v234
	v_fma_f32 v54, v156, v70, v88
	v_and_b32_e32 v156, 0xffff0000, v155
	v_sub_f32_e32 v156, v156, v224
	v_mul_f32_e32 v156, v156, v234
	v_fma_f32 v55, v156, v71, v89
	v_cndmask_b32_e64 v152, v56, v60, s[58:59]
	v_cndmask_b32_e64 v153, v57, v61, s[58:59]
	v_cndmask_b32_e64 v154, v58, v62, s[58:59]
	v_cndmask_b32_e64 v155, v59, v63, s[58:59]
	v_lshlrev_b32_e32 v156, 16, v152
	v_sub_f32_e32 v156, v156, v225
	v_mul_f32_e32 v156, v156, v235
	v_fma_f32 v56, v156, v64, v82
	v_and_b32_e32 v156, 0xffff0000, v152
	v_sub_f32_e32 v156, v156, v225
	v_mul_f32_e32 v156, v156, v235
	v_fma_f32 v57, v156, v65, v83
	v_lshlrev_b32_e32 v156, 16, v153
	v_sub_f32_e32 v156, v156, v225
	v_mul_f32_e32 v156, v156, v235
	v_fma_f32 v58, v156, v66, v84
	v_and_b32_e32 v156, 0xffff0000, v153
	v_sub_f32_e32 v156, v156, v225
	v_mul_f32_e32 v156, v156, v235
	v_fma_f32 v59, v156, v67, v85
	v_lshlrev_b32_e32 v156, 16, v154
	v_sub_f32_e32 v156, v156, v225
	v_mul_f32_e32 v156, v156, v235
	v_fma_f32 v60, v156, v68, v86
	v_and_b32_e32 v156, 0xffff0000, v154
	v_sub_f32_e32 v156, v156, v225
	v_mul_f32_e32 v156, v156, v235
	v_fma_f32 v61, v156, v69, v87
	v_lshlrev_b32_e32 v156, 16, v155
	v_sub_f32_e32 v156, v156, v225
	v_mul_f32_e32 v156, v156, v235
	v_fma_f32 v62, v156, v70, v88
	v_and_b32_e32 v156, 0xffff0000, v155
	v_sub_f32_e32 v156, v156, v225
	v_mul_f32_e32 v156, v156, v235
	v_fma_f32 v63, v156, v71, v89
	s_waitcnt vmcnt(0)
	s_lshl_b32 s60, s57, 15
	s_add_u32 s54, s38, s60
	s_addc_u32 s55, s39, 0
	s_add_u32 s54, s54, 0x2000000
	s_addc_u32 s55, s55, 0
	v_mov_b32_e32 v152, v90
	v_mov_b32_e32 v153, v90
	v_mov_b32_e32 v154, v90
	v_mov_b32_e32 v155, v90
	v_mov_b32_e32 v156, v90
	v_mov_b32_e32 v157, v90
	v_mov_b32_e32 v158, v90
	v_mov_b32_e32 v159, v90
	v_fmac_f32_e32 v152, v166, v0
	v_fmac_f32_e32 v153, v166, v1
	v_fmac_f32_e32 v154, v166, v2
	v_fmac_f32_e32 v155, v166, v3
	v_fmac_f32_e32 v156, v166, v4
	v_fmac_f32_e32 v157, v166, v5
	v_fmac_f32_e32 v158, v166, v6
	v_fmac_f32_e32 v159, v166, v7
	v_lshlrev_b32_e32 v244, 16, v98
	v_and_b32_e32 v245, 0xffff0000, v98
	v_mul_f32_e32 v244, v244, v152
	v_mul_f32_e32 v245, v245, v153
	v_cvt_pk_bf16_f32 v98, v244, v245
	v_lshlrev_b32_e32 v244, 16, v99
	v_and_b32_e32 v245, 0xffff0000, v99
	v_mul_f32_e32 v244, v244, v154
	v_mul_f32_e32 v245, v245, v155
	v_cvt_pk_bf16_f32 v99, v244, v245
	v_lshlrev_b32_e32 v244, 16, v100
	v_and_b32_e32 v245, 0xffff0000, v100
	v_mul_f32_e32 v244, v244, v156
	v_mul_f32_e32 v245, v245, v157
	v_cvt_pk_bf16_f32 v100, v244, v245
	v_lshlrev_b32_e32 v244, 16, v101
	v_and_b32_e32 v245, 0xffff0000, v101
	v_mul_f32_e32 v244, v244, v158
	v_mul_f32_e32 v245, v245, v159
	v_cvt_pk_bf16_f32 v101, v244, v245
	global_store_dwordx4 v163, v[98:101], s[54:55]
	s_add_u32 s54, s54, 0x1000
	s_addc_u32 s55, s55, 0
	v_mov_b32_e32 v152, v91
	v_mov_b32_e32 v153, v91
	v_mov_b32_e32 v154, v91
	v_mov_b32_e32 v155, v91
	v_mov_b32_e32 v156, v91
	v_mov_b32_e32 v157, v91
	v_mov_b32_e32 v158, v91
	v_mov_b32_e32 v159, v91
	v_fmac_f32_e32 v152, v174, v0
	v_fmac_f32_e32 v153, v174, v1
	v_fmac_f32_e32 v154, v174, v2
	v_fmac_f32_e32 v155, v174, v3
	v_fmac_f32_e32 v156, v174, v4
	v_fmac_f32_e32 v157, v174, v5
	v_fmac_f32_e32 v158, v174, v6
	v_fmac_f32_e32 v159, v174, v7
	v_fmac_f32_e32 v152, v175, v8
	v_fmac_f32_e32 v153, v175, v9
	v_fmac_f32_e32 v154, v175, v10
	v_fmac_f32_e32 v155, v175, v11
	v_fmac_f32_e32 v156, v175, v12
	v_fmac_f32_e32 v157, v175, v13
	v_fmac_f32_e32 v158, v175, v14
	v_fmac_f32_e32 v159, v175, v15
	v_lshlrev_b32_e32 v244, 16, v102
	v_and_b32_e32 v245, 0xffff0000, v102
	v_mul_f32_e32 v244, v244, v152
	v_mul_f32_e32 v245, v245, v153
	v_cvt_pk_bf16_f32 v102, v244, v245
	v_lshlrev_b32_e32 v244, 16, v103
	v_and_b32_e32 v245, 0xffff0000, v103
	v_mul_f32_e32 v244, v244, v154
	v_mul_f32_e32 v245, v245, v155
	v_cvt_pk_bf16_f32 v103, v244, v245
	v_lshlrev_b32_e32 v244, 16, v104
	v_and_b32_e32 v245, 0xffff0000, v104
	v_mul_f32_e32 v244, v244, v156
	v_mul_f32_e32 v245, v245, v157
	v_cvt_pk_bf16_f32 v104, v244, v245
	v_lshlrev_b32_e32 v244, 16, v105
	v_and_b32_e32 v245, 0xffff0000, v105
	v_mul_f32_e32 v244, v244, v158
	v_mul_f32_e32 v245, v245, v159
	v_cvt_pk_bf16_f32 v105, v244, v245
	global_store_dwordx4 v163, v[102:105], s[54:55]
	s_add_u32 s54, s54, 0x1000
	s_addc_u32 s55, s55, 0
	v_mov_b32_e32 v152, v92
	v_mov_b32_e32 v153, v92
	v_mov_b32_e32 v154, v92
	v_mov_b32_e32 v155, v92
	v_mov_b32_e32 v156, v92
	v_mov_b32_e32 v157, v92
	v_mov_b32_e32 v158, v92
	v_mov_b32_e32 v159, v92
	v_fmac_f32_e32 v152, v182, v0
	v_fmac_f32_e32 v153, v182, v1
	v_fmac_f32_e32 v154, v182, v2
	v_fmac_f32_e32 v155, v182, v3
	v_fmac_f32_e32 v156, v182, v4
	v_fmac_f32_e32 v157, v182, v5
	v_fmac_f32_e32 v158, v182, v6
	v_fmac_f32_e32 v159, v182, v7
	v_fmac_f32_e32 v152, v183, v8
	v_fmac_f32_e32 v153, v183, v9
	v_fmac_f32_e32 v154, v183, v10
	v_fmac_f32_e32 v155, v183, v11
	v_fmac_f32_e32 v156, v183, v12
	v_fmac_f32_e32 v157, v183, v13
	v_fmac_f32_e32 v158, v183, v14
	v_fmac_f32_e32 v159, v183, v15
	v_fmac_f32_e32 v152, v184, v16
	v_fmac_f32_e32 v153, v184, v17
	v_fmac_f32_e32 v154, v184, v18
	v_fmac_f32_e32 v155, v184, v19
	v_fmac_f32_e32 v156, v184, v20
	v_fmac_f32_e32 v157, v184, v21
	v_fmac_f32_e32 v158, v184, v22
	v_fmac_f32_e32 v159, v184, v23
	v_lshlrev_b32_e32 v244, 16, v106
	v_and_b32_e32 v245, 0xffff0000, v106
	v_mul_f32_e32 v244, v244, v152
	v_mul_f32_e32 v245, v245, v153
	v_cvt_pk_bf16_f32 v106, v244, v245
	v_lshlrev_b32_e32 v244, 16, v107
	v_and_b32_e32 v245, 0xffff0000, v107
	v_mul_f32_e32 v244, v244, v154
	v_mul_f32_e32 v245, v245, v155
	v_cvt_pk_bf16_f32 v107, v244, v245
	v_lshlrev_b32_e32 v244, 16, v108
	v_and_b32_e32 v245, 0xffff0000, v108
	v_mul_f32_e32 v244, v244, v156
	v_mul_f32_e32 v245, v245, v157
	v_cvt_pk_bf16_f32 v108, v244, v245
	v_lshlrev_b32_e32 v244, 16, v109
	v_and_b32_e32 v245, 0xffff0000, v109
	v_mul_f32_e32 v244, v244, v158
	v_mul_f32_e32 v245, v245, v159
	v_cvt_pk_bf16_f32 v109, v244, v245
	global_store_dwordx4 v163, v[106:109], s[54:55]
	s_add_u32 s54, s54, 0x1000
	s_addc_u32 s55, s55, 0
	v_mov_b32_e32 v152, v93
	v_mov_b32_e32 v153, v93
	v_mov_b32_e32 v154, v93
	v_mov_b32_e32 v155, v93
	v_mov_b32_e32 v156, v93
	v_mov_b32_e32 v157, v93
	v_mov_b32_e32 v158, v93
	v_mov_b32_e32 v159, v93
	v_fmac_f32_e32 v152, v190, v0
	v_fmac_f32_e32 v153, v190, v1
	v_fmac_f32_e32 v154, v190, v2
	v_fmac_f32_e32 v155, v190, v3
	v_fmac_f32_e32 v156, v190, v4
	v_fmac_f32_e32 v157, v190, v5
	v_fmac_f32_e32 v158, v190, v6
	v_fmac_f32_e32 v159, v190, v7
	v_fmac_f32_e32 v152, v191, v8
	v_fmac_f32_e32 v153, v191, v9
	v_fmac_f32_e32 v154, v191, v10
	v_fmac_f32_e32 v155, v191, v11
	v_fmac_f32_e32 v156, v191, v12
	v_fmac_f32_e32 v157, v191, v13
	v_fmac_f32_e32 v158, v191, v14
	v_fmac_f32_e32 v159, v191, v15
	v_fmac_f32_e32 v152, v192, v16
	v_fmac_f32_e32 v153, v192, v17
	v_fmac_f32_e32 v154, v192, v18
	v_fmac_f32_e32 v155, v192, v19
	v_fmac_f32_e32 v156, v192, v20
	v_fmac_f32_e32 v157, v192, v21
	v_fmac_f32_e32 v158, v192, v22
	v_fmac_f32_e32 v159, v192, v23
	v_fmac_f32_e32 v152, v193, v24
	v_fmac_f32_e32 v153, v193, v25
	v_fmac_f32_e32 v154, v193, v26
	v_fmac_f32_e32 v155, v193, v27
	v_fmac_f32_e32 v156, v193, v28
	v_fmac_f32_e32 v157, v193, v29
	v_fmac_f32_e32 v158, v193, v30
	v_fmac_f32_e32 v159, v193, v31
	v_lshlrev_b32_e32 v244, 16, v110
	v_and_b32_e32 v245, 0xffff0000, v110
	v_mul_f32_e32 v244, v244, v152
	v_mul_f32_e32 v245, v245, v153
	v_cvt_pk_bf16_f32 v110, v244, v245
	v_lshlrev_b32_e32 v244, 16, v111
	v_and_b32_e32 v245, 0xffff0000, v111
	v_mul_f32_e32 v244, v244, v154
	v_mul_f32_e32 v245, v245, v155
	v_cvt_pk_bf16_f32 v111, v244, v245
	v_lshlrev_b32_e32 v244, 16, v112
	v_and_b32_e32 v245, 0xffff0000, v112
	v_mul_f32_e32 v244, v244, v156
	v_mul_f32_e32 v245, v245, v157
	v_cvt_pk_bf16_f32 v112, v244, v245
	v_lshlrev_b32_e32 v244, 16, v113
	v_and_b32_e32 v245, 0xffff0000, v113
	v_mul_f32_e32 v244, v244, v158
	v_mul_f32_e32 v245, v245, v159
	v_cvt_pk_bf16_f32 v113, v244, v245
	global_store_dwordx4 v163, v[110:113], s[54:55]
	s_add_u32 s54, s54, 0x1000
	s_addc_u32 s55, s55, 0
	v_mov_b32_e32 v152, v94
	v_mov_b32_e32 v153, v94
	v_mov_b32_e32 v154, v94
	v_mov_b32_e32 v155, v94
	v_mov_b32_e32 v156, v94
	v_mov_b32_e32 v157, v94
	v_mov_b32_e32 v158, v94
	v_mov_b32_e32 v159, v94
	v_fmac_f32_e32 v152, v198, v0
	v_fmac_f32_e32 v153, v198, v1
	v_fmac_f32_e32 v154, v198, v2
	v_fmac_f32_e32 v155, v198, v3
	v_fmac_f32_e32 v156, v198, v4
	v_fmac_f32_e32 v157, v198, v5
	v_fmac_f32_e32 v158, v198, v6
	v_fmac_f32_e32 v159, v198, v7
	v_fmac_f32_e32 v152, v199, v8
	v_fmac_f32_e32 v153, v199, v9
	v_fmac_f32_e32 v154, v199, v10
	v_fmac_f32_e32 v155, v199, v11
	v_fmac_f32_e32 v156, v199, v12
	v_fmac_f32_e32 v157, v199, v13
	v_fmac_f32_e32 v158, v199, v14
	v_fmac_f32_e32 v159, v199, v15
	v_fmac_f32_e32 v152, v200, v16
	v_fmac_f32_e32 v153, v200, v17
	v_fmac_f32_e32 v154, v200, v18
	v_fmac_f32_e32 v155, v200, v19
	v_fmac_f32_e32 v156, v200, v20
	v_fmac_f32_e32 v157, v200, v21
	v_fmac_f32_e32 v158, v200, v22
	v_fmac_f32_e32 v159, v200, v23
	v_fmac_f32_e32 v152, v201, v24
	v_fmac_f32_e32 v153, v201, v25
	v_fmac_f32_e32 v154, v201, v26
	v_fmac_f32_e32 v155, v201, v27
	v_fmac_f32_e32 v156, v201, v28
	v_fmac_f32_e32 v157, v201, v29
	v_fmac_f32_e32 v158, v201, v30
	v_fmac_f32_e32 v159, v201, v31
	v_fmac_f32_e32 v152, v202, v32
	v_fmac_f32_e32 v153, v202, v33
	v_fmac_f32_e32 v154, v202, v34
	v_fmac_f32_e32 v155, v202, v35
	v_fmac_f32_e32 v156, v202, v36
	v_fmac_f32_e32 v157, v202, v37
	v_fmac_f32_e32 v158, v202, v38
	v_fmac_f32_e32 v159, v202, v39
	v_lshlrev_b32_e32 v244, 16, v114
	v_and_b32_e32 v245, 0xffff0000, v114
	v_mul_f32_e32 v244, v244, v152
	v_mul_f32_e32 v245, v245, v153
	v_cvt_pk_bf16_f32 v114, v244, v245
	v_lshlrev_b32_e32 v244, 16, v115
	v_and_b32_e32 v245, 0xffff0000, v115
	v_mul_f32_e32 v244, v244, v154
	v_mul_f32_e32 v245, v245, v155
	v_cvt_pk_bf16_f32 v115, v244, v245
	v_lshlrev_b32_e32 v244, 16, v116
	v_and_b32_e32 v245, 0xffff0000, v116
	v_mul_f32_e32 v244, v244, v156
	v_mul_f32_e32 v245, v245, v157
	v_cvt_pk_bf16_f32 v116, v244, v245
	v_lshlrev_b32_e32 v244, 16, v117
	v_and_b32_e32 v245, 0xffff0000, v117
	v_mul_f32_e32 v244, v244, v158
	v_mul_f32_e32 v245, v245, v159
	v_cvt_pk_bf16_f32 v117, v244, v245
	global_store_dwordx4 v163, v[114:117], s[54:55]
	s_add_u32 s54, s54, 0x1000
	s_addc_u32 s55, s55, 0
	v_mov_b32_e32 v152, v95
	v_mov_b32_e32 v153, v95
	v_mov_b32_e32 v154, v95
	v_mov_b32_e32 v155, v95
	v_mov_b32_e32 v156, v95
	v_mov_b32_e32 v157, v95
	v_mov_b32_e32 v158, v95
	v_mov_b32_e32 v159, v95
	v_fmac_f32_e32 v152, v206, v0
	v_fmac_f32_e32 v153, v206, v1
	v_fmac_f32_e32 v154, v206, v2
	v_fmac_f32_e32 v155, v206, v3
	v_fmac_f32_e32 v156, v206, v4
	v_fmac_f32_e32 v157, v206, v5
	v_fmac_f32_e32 v158, v206, v6
	v_fmac_f32_e32 v159, v206, v7
	v_fmac_f32_e32 v152, v207, v8
	v_fmac_f32_e32 v153, v207, v9
	v_fmac_f32_e32 v154, v207, v10
	v_fmac_f32_e32 v155, v207, v11
	v_fmac_f32_e32 v156, v207, v12
	v_fmac_f32_e32 v157, v207, v13
	v_fmac_f32_e32 v158, v207, v14
	v_fmac_f32_e32 v159, v207, v15
	v_fmac_f32_e32 v152, v208, v16
	v_fmac_f32_e32 v153, v208, v17
	v_fmac_f32_e32 v154, v208, v18
	v_fmac_f32_e32 v155, v208, v19
	v_fmac_f32_e32 v156, v208, v20
	v_fmac_f32_e32 v157, v208, v21
	v_fmac_f32_e32 v158, v208, v22
	v_fmac_f32_e32 v159, v208, v23
	v_fmac_f32_e32 v152, v209, v24
	v_fmac_f32_e32 v153, v209, v25
	v_fmac_f32_e32 v154, v209, v26
	v_fmac_f32_e32 v155, v209, v27
	v_fmac_f32_e32 v156, v209, v28
	v_fmac_f32_e32 v157, v209, v29
	v_fmac_f32_e32 v158, v209, v30
	v_fmac_f32_e32 v159, v209, v31
	v_fmac_f32_e32 v152, v210, v32
	v_fmac_f32_e32 v153, v210, v33
	v_fmac_f32_e32 v154, v210, v34
	v_fmac_f32_e32 v155, v210, v35
	v_fmac_f32_e32 v156, v210, v36
	v_fmac_f32_e32 v157, v210, v37
	v_fmac_f32_e32 v158, v210, v38
	v_fmac_f32_e32 v159, v210, v39
	v_fmac_f32_e32 v152, v211, v40
	v_fmac_f32_e32 v153, v211, v41
	v_fmac_f32_e32 v154, v211, v42
	v_fmac_f32_e32 v155, v211, v43
	v_fmac_f32_e32 v156, v211, v44
	v_fmac_f32_e32 v157, v211, v45
	v_fmac_f32_e32 v158, v211, v46
	v_fmac_f32_e32 v159, v211, v47
	v_lshlrev_b32_e32 v244, 16, v118
	v_and_b32_e32 v245, 0xffff0000, v118
	v_mul_f32_e32 v244, v244, v152
	v_mul_f32_e32 v245, v245, v153
	v_cvt_pk_bf16_f32 v118, v244, v245
	v_lshlrev_b32_e32 v244, 16, v119
	v_and_b32_e32 v245, 0xffff0000, v119
	v_mul_f32_e32 v244, v244, v154
	v_mul_f32_e32 v245, v245, v155
	v_cvt_pk_bf16_f32 v119, v244, v245
	v_lshlrev_b32_e32 v244, 16, v120
	v_and_b32_e32 v245, 0xffff0000, v120
	v_mul_f32_e32 v244, v244, v156
	v_mul_f32_e32 v245, v245, v157
	v_cvt_pk_bf16_f32 v120, v244, v245
	v_lshlrev_b32_e32 v244, 16, v121
	v_and_b32_e32 v245, 0xffff0000, v121
	v_mul_f32_e32 v244, v244, v158
	v_mul_f32_e32 v245, v245, v159
	v_cvt_pk_bf16_f32 v121, v244, v245
	global_store_dwordx4 v163, v[118:121], s[54:55]
	s_add_u32 s54, s54, 0x1000
	s_addc_u32 s55, s55, 0
	v_mov_b32_e32 v152, v96
	v_mov_b32_e32 v153, v96
	v_mov_b32_e32 v154, v96
	v_mov_b32_e32 v155, v96
	v_mov_b32_e32 v156, v96
	v_mov_b32_e32 v157, v96
	v_mov_b32_e32 v158, v96
	v_mov_b32_e32 v159, v96
	v_fmac_f32_e32 v152, v136, v0
	v_fmac_f32_e32 v153, v136, v1
	v_fmac_f32_e32 v154, v136, v2
	v_fmac_f32_e32 v155, v136, v3
	v_fmac_f32_e32 v156, v136, v4
	v_fmac_f32_e32 v157, v136, v5
	v_fmac_f32_e32 v158, v136, v6
	v_fmac_f32_e32 v159, v136, v7
	v_fmac_f32_e32 v152, v137, v8
	v_fmac_f32_e32 v153, v137, v9
	v_fmac_f32_e32 v154, v137, v10
	v_fmac_f32_e32 v155, v137, v11
	v_fmac_f32_e32 v156, v137, v12
	v_fmac_f32_e32 v157, v137, v13
	v_fmac_f32_e32 v158, v137, v14
	v_fmac_f32_e32 v159, v137, v15
	v_fmac_f32_e32 v152, v138, v16
	v_fmac_f32_e32 v153, v138, v17
	v_fmac_f32_e32 v154, v138, v18
	v_fmac_f32_e32 v155, v138, v19
	v_fmac_f32_e32 v156, v138, v20
	v_fmac_f32_e32 v157, v138, v21
	v_fmac_f32_e32 v158, v138, v22
	v_fmac_f32_e32 v159, v138, v23
	v_fmac_f32_e32 v152, v139, v24
	v_fmac_f32_e32 v153, v139, v25
	v_fmac_f32_e32 v154, v139, v26
	v_fmac_f32_e32 v155, v139, v27
	v_fmac_f32_e32 v156, v139, v28
	v_fmac_f32_e32 v157, v139, v29
	v_fmac_f32_e32 v158, v139, v30
	v_fmac_f32_e32 v159, v139, v31
	v_fmac_f32_e32 v152, v140, v32
	v_fmac_f32_e32 v153, v140, v33
	v_fmac_f32_e32 v154, v140, v34
	v_fmac_f32_e32 v155, v140, v35
	v_fmac_f32_e32 v156, v140, v36
	v_fmac_f32_e32 v157, v140, v37
	v_fmac_f32_e32 v158, v140, v38
	v_fmac_f32_e32 v159, v140, v39
	v_fmac_f32_e32 v152, v141, v40
	v_fmac_f32_e32 v153, v141, v41
	v_fmac_f32_e32 v154, v141, v42
	v_fmac_f32_e32 v155, v141, v43
	v_fmac_f32_e32 v156, v141, v44
	v_fmac_f32_e32 v157, v141, v45
	v_fmac_f32_e32 v158, v141, v46
	v_fmac_f32_e32 v159, v141, v47
	v_fmac_f32_e32 v152, v142, v48
	v_fmac_f32_e32 v153, v142, v49
	v_fmac_f32_e32 v154, v142, v50
	v_fmac_f32_e32 v155, v142, v51
	v_fmac_f32_e32 v156, v142, v52
	v_fmac_f32_e32 v157, v142, v53
	v_fmac_f32_e32 v158, v142, v54
	v_fmac_f32_e32 v159, v142, v55
	v_lshlrev_b32_e32 v244, 16, v122
	v_and_b32_e32 v245, 0xffff0000, v122
	v_mul_f32_e32 v244, v244, v152
	v_mul_f32_e32 v245, v245, v153
	v_cvt_pk_bf16_f32 v122, v244, v245
	v_lshlrev_b32_e32 v244, 16, v123
	v_and_b32_e32 v245, 0xffff0000, v123
	v_mul_f32_e32 v244, v244, v154
	v_mul_f32_e32 v245, v245, v155
	v_cvt_pk_bf16_f32 v123, v244, v245
	v_lshlrev_b32_e32 v244, 16, v124
	v_and_b32_e32 v245, 0xffff0000, v124
	v_mul_f32_e32 v244, v244, v156
	v_mul_f32_e32 v245, v245, v157
	v_cvt_pk_bf16_f32 v124, v244, v245
	v_lshlrev_b32_e32 v244, 16, v125
	v_and_b32_e32 v245, 0xffff0000, v125
	v_mul_f32_e32 v244, v244, v158
	v_mul_f32_e32 v245, v245, v159
	v_cvt_pk_bf16_f32 v125, v244, v245
	global_store_dwordx4 v163, v[122:125], s[54:55]
	s_add_u32 s54, s54, 0x1000
	s_addc_u32 s55, s55, 0
	v_mov_b32_e32 v152, v97
	v_mov_b32_e32 v153, v97
	v_mov_b32_e32 v154, v97
	v_mov_b32_e32 v155, v97
	v_mov_b32_e32 v156, v97
	v_mov_b32_e32 v157, v97
	v_mov_b32_e32 v158, v97
	v_mov_b32_e32 v159, v97
	v_fmac_f32_e32 v152, v144, v0
	v_fmac_f32_e32 v153, v144, v1
	v_fmac_f32_e32 v154, v144, v2
	v_fmac_f32_e32 v155, v144, v3
	v_fmac_f32_e32 v156, v144, v4
	v_fmac_f32_e32 v157, v144, v5
	v_fmac_f32_e32 v158, v144, v6
	v_fmac_f32_e32 v159, v144, v7
	v_fmac_f32_e32 v152, v145, v8
	v_fmac_f32_e32 v153, v145, v9
	v_fmac_f32_e32 v154, v145, v10
	v_fmac_f32_e32 v155, v145, v11
	v_fmac_f32_e32 v156, v145, v12
	v_fmac_f32_e32 v157, v145, v13
	v_fmac_f32_e32 v158, v145, v14
	v_fmac_f32_e32 v159, v145, v15
	v_fmac_f32_e32 v152, v146, v16
	v_fmac_f32_e32 v153, v146, v17
	v_fmac_f32_e32 v154, v146, v18
	v_fmac_f32_e32 v155, v146, v19
	v_fmac_f32_e32 v156, v146, v20
	v_fmac_f32_e32 v157, v146, v21
	v_fmac_f32_e32 v158, v146, v22
	v_fmac_f32_e32 v159, v146, v23
	v_fmac_f32_e32 v152, v147, v24
	v_fmac_f32_e32 v153, v147, v25
	v_fmac_f32_e32 v154, v147, v26
	v_fmac_f32_e32 v155, v147, v27
	v_fmac_f32_e32 v156, v147, v28
	v_fmac_f32_e32 v157, v147, v29
	v_fmac_f32_e32 v158, v147, v30
	v_fmac_f32_e32 v159, v147, v31
	v_fmac_f32_e32 v152, v148, v32
	v_fmac_f32_e32 v153, v148, v33
	v_fmac_f32_e32 v154, v148, v34
	v_fmac_f32_e32 v155, v148, v35
	v_fmac_f32_e32 v156, v148, v36
	v_fmac_f32_e32 v157, v148, v37
	v_fmac_f32_e32 v158, v148, v38
	v_fmac_f32_e32 v159, v148, v39
	v_fmac_f32_e32 v152, v149, v40
	v_fmac_f32_e32 v153, v149, v41
	v_fmac_f32_e32 v154, v149, v42
	v_fmac_f32_e32 v155, v149, v43
	v_fmac_f32_e32 v156, v149, v44
	v_fmac_f32_e32 v157, v149, v45
	v_fmac_f32_e32 v158, v149, v46
	v_fmac_f32_e32 v159, v149, v47
	v_fmac_f32_e32 v152, v150, v48
	v_fmac_f32_e32 v153, v150, v49
	v_fmac_f32_e32 v154, v150, v50
	v_fmac_f32_e32 v155, v150, v51
	v_fmac_f32_e32 v156, v150, v52
	v_fmac_f32_e32 v157, v150, v53
	v_fmac_f32_e32 v158, v150, v54
	v_fmac_f32_e32 v159, v150, v55
	v_fmac_f32_e32 v152, v151, v56
	v_fmac_f32_e32 v153, v151, v57
	v_fmac_f32_e32 v154, v151, v58
	v_fmac_f32_e32 v155, v151, v59
	v_fmac_f32_e32 v156, v151, v60
	v_fmac_f32_e32 v157, v151, v61
	v_fmac_f32_e32 v158, v151, v62
	v_fmac_f32_e32 v159, v151, v63
	v_lshlrev_b32_e32 v244, 16, v214
	v_and_b32_e32 v245, 0xffff0000, v214
	v_mul_f32_e32 v244, v244, v152
	v_mul_f32_e32 v245, v245, v153
	v_cvt_pk_bf16_f32 v214, v244, v245
	v_lshlrev_b32_e32 v244, 16, v215
	v_and_b32_e32 v245, 0xffff0000, v215
	v_mul_f32_e32 v244, v244, v154
	v_mul_f32_e32 v245, v245, v155
	v_cvt_pk_bf16_f32 v215, v244, v245
	v_lshlrev_b32_e32 v244, 16, v216
	v_and_b32_e32 v245, 0xffff0000, v216
	v_mul_f32_e32 v244, v244, v156
	v_mul_f32_e32 v245, v245, v157
	v_cvt_pk_bf16_f32 v216, v244, v245
	v_lshlrev_b32_e32 v244, 16, v217
	v_and_b32_e32 v245, 0xffff0000, v217
	v_mul_f32_e32 v244, v244, v158
	v_mul_f32_e32 v245, v245, v159
	v_cvt_pk_bf16_f32 v217, v244, v245
	global_store_dwordx4 v163, v[214:217], s[54:55]
	s_lshl_b32 s60, s57, 15
	s_add_u32 s52, s7, s60
	s_addc_u32 s53, s9, 0
	global_store_dwordx4 v135, v[0:3], s[52:53]
	global_store_dwordx4 v135, v[4:7], s[52:53] offset:16
	s_add_u32 s52, s52, 0x1000
	s_addc_u32 s53, s53, 0
	global_store_dwordx4 v135, v[8:11], s[52:53]
	global_store_dwordx4 v135, v[12:15], s[52:53] offset:16
	s_add_u32 s52, s52, 0x1000
	s_addc_u32 s53, s53, 0
	global_store_dwordx4 v135, v[16:19], s[52:53]
	global_store_dwordx4 v135, v[20:23], s[52:53] offset:16
	s_add_u32 s52, s52, 0x1000
	s_addc_u32 s53, s53, 0
	global_store_dwordx4 v135, v[24:27], s[52:53]
	global_store_dwordx4 v135, v[28:31], s[52:53] offset:16
	s_add_u32 s52, s52, 0x1000
	s_addc_u32 s53, s53, 0
	global_store_dwordx4 v135, v[32:35], s[52:53]
	global_store_dwordx4 v135, v[36:39], s[52:53] offset:16
	s_add_u32 s52, s52, 0x1000
	s_addc_u32 s53, s53, 0
	global_store_dwordx4 v135, v[40:43], s[52:53]
	global_store_dwordx4 v135, v[44:47], s[52:53] offset:16
	s_add_u32 s52, s52, 0x1000
	s_addc_u32 s53, s53, 0
	global_store_dwordx4 v135, v[48:51], s[52:53]
	global_store_dwordx4 v135, v[52:55], s[52:53] offset:16
	s_add_u32 s52, s52, 0x1000
	s_addc_u32 s53, s53, 0
	global_store_dwordx4 v135, v[56:59], s[52:53]
	global_store_dwordx4 v135, v[60:63], s[52:53] offset:16
	s_branch .LBB0_343
